# loop-edge variant plus s_setprio moved ahead of the opening barrier and the redundant post-barrier lgkmcnt wait removed (first MFMA issues right after barrier release)
# speedup vs baseline: 1.0054x; 1.0054x over previous
.LBB0_1516:
	v_add_u32_e32 v156, s83, v142
	v_add_u32_e32 v172, s44, v142
	s_add_u32 s8, s37, s6
	ds_read_b128 v[144:147], v156
	ds_read_b128 v[148:151], v156 offset:1024
	ds_read_b128 v[152:155], v156 offset:2048
	ds_read_b128 v[156:159], v156 offset:3072
	ds_read_b128 v[160:163], v172
	ds_read_b128 v[164:167], v172 offset:1024
	ds_read_b128 v[168:171], v172 offset:2048
	ds_read_b128 v[172:175], v172 offset:3072
	s_addc_u32 s9, s40, s7
	s_add_u32 s8, s8, 0x20400100
	s_addc_u32 s9, s9, 0
	s_add_u32 s46, s41, s6
	s_addc_u32 s47, s42, s7
	s_cmpk_eq_i32 s6, 0xf00
	s_cselect_b32 s11, s5, s9
	s_cselect_b32 s10, s4, s8
	s_cselect_b32 s9, s3, s47
	s_cselect_b32 s8, s2, s46
	v_lshl_add_u64 v[208:209], v[138:139], 0, s[6:7]
	s_add_i32 m0, s16, 0xc000
	ds_read_b128 v[176:179], v143
	ds_read_b128 v[180:183], v143 offset:1024
	ds_read_b128 v[184:187], v143 offset:2048
	ds_read_b128 v[188:191], v143 offset:3072
	ds_read_b128 v[192:195], v143 offset:4096
	ds_read_b128 v[196:199], v143 offset:5120
	ds_read_b128 v[200:203], v143 offset:6144
	ds_read_b128 v[204:207], v143 offset:7168
	global_load_lds_dwordx4 v[208:209], off
	v_lshl_add_u64 v[208:209], v[140:141], 0, s[6:7]
	s_add_i32 m0, s16, 0xe000
	s_nop 0
	global_load_lds_dwordx4 v[208:209], off
	s_waitcnt vmcnt(8)
	s_waitcnt lgkmcnt(0)
	s_setprio 1
	s_barrier
	s_cmp_lg_u32 s101, 0
	s_cbranch_scc1 .Lt13a_0
	v_mfma_f32_16x16x32_bf16 v[128:131], v[144:147], v[176:179], v[128:131]
	v_mfma_f32_16x16x32_bf16 v[128:131], v[148:151], v[180:183], v[128:131]
	v_mfma_f32_16x16x32_bf16 v[112:115], v[144:147], v[184:187], v[112:115]
	v_mfma_f32_16x16x32_bf16 v[112:115], v[148:151], v[188:191], v[112:115]
	v_mfma_f32_16x16x32_bf16 v[96:99], v[144:147], v[192:195], v[96:99]
	v_mfma_f32_16x16x32_bf16 v[96:99], v[148:151], v[196:199], v[96:99]
	v_mfma_f32_16x16x32_bf16 v[80:83], v[144:147], v[200:203], v[80:83]
	v_mfma_f32_16x16x32_bf16 v[80:83], v[148:151], v[204:207], v[80:83]
	v_mfma_f32_16x16x32_bf16 v[76:79], v[152:155], v[200:203], v[76:79]
	v_mfma_f32_16x16x32_bf16 v[76:79], v[156:159], v[204:207], v[76:79]
	v_mfma_f32_16x16x32_bf16 v[92:95], v[152:155], v[192:195], v[92:95]
	v_mfma_f32_16x16x32_bf16 v[92:95], v[156:159], v[196:199], v[92:95]
	v_mfma_f32_16x16x32_bf16 v[108:111], v[152:155], v[184:187], v[108:111]
	v_mfma_f32_16x16x32_bf16 v[108:111], v[156:159], v[188:191], v[108:111]
	v_mfma_f32_16x16x32_bf16 v[124:127], v[152:155], v[176:179], v[124:127]
	v_mfma_f32_16x16x32_bf16 v[124:127], v[156:159], v[180:183], v[124:127]

.Lt13b_0:
	s_setprio 0
	s_barrier
	s_mov_b32 m0, s13
	v_lshl_add_u64 v[208:209], s[8:9], 0, v[2:3]
	s_add_u32 s46, s8, 0x80000
	ds_read_b128 v[176:179], v143 offset:16384
	ds_read_b128 v[180:183], v143 offset:17408
	ds_read_b128 v[184:187], v143 offset:18432
	ds_read_b128 v[188:191], v143 offset:19456
	ds_read_b128 v[192:195], v143 offset:20480
	ds_read_b128 v[196:199], v143 offset:21504
	ds_read_b128 v[200:203], v143 offset:22528
	ds_read_b128 v[204:207], v143 offset:23552
	global_load_lds_dwordx4 v[208:209], off
	v_lshl_add_u64 v[210:211], s[8:9], 0, v[136:137]
	s_mov_b32 m0, s14
	s_addc_u32 s47, s9, 0
	global_load_lds_dwordx4 v[210:211], off
	v_lshl_add_u64 v[216:217], s[46:47], 0, v[2:3]
	s_mov_b32 m0, s15
	v_lshl_add_u64 v[218:219], s[10:11], 0, v[134:135]
	global_load_lds_dwordx4 v[216:217], off
	v_lshl_add_u64 v[216:217], s[46:47], 0, v[136:137]
	s_mov_b32 m0, s19
	s_nop 0
	global_load_lds_dwordx4 v[216:217], off
	v_lshl_add_u64 v[216:217], s[10:11], 0, v[132:133]
	s_mov_b32 m0, s16
	s_nop 0
	global_load_lds_dwordx4 v[216:217], off
	s_mov_b32 m0, s20
	s_nop 0
	global_load_lds_dwordx4 v[218:219], off
	s_waitcnt vmcnt(8)
	s_waitcnt lgkmcnt(0)
	s_setprio 1
	s_barrier
	s_cmp_lg_u32 s101, 0
	s_cbranch_scc1 .Lt13a_1
	v_mfma_f32_16x16x32_bf16 v[64:67], v[144:147], v[176:179], v[64:67]
	v_mfma_f32_16x16x32_bf16 v[64:67], v[148:151], v[180:183], v[64:67]
	v_mfma_f32_16x16x32_bf16 v[48:51], v[144:147], v[184:187], v[48:51]
	v_mfma_f32_16x16x32_bf16 v[48:51], v[148:151], v[188:191], v[48:51]
	v_mfma_f32_16x16x32_bf16 v[32:35], v[144:147], v[192:195], v[32:35]
	v_mfma_f32_16x16x32_bf16 v[32:35], v[148:151], v[196:199], v[32:35]
	v_mfma_f32_16x16x32_bf16 v[16:19], v[144:147], v[200:203], v[16:19]
	v_mfma_f32_16x16x32_bf16 v[16:19], v[148:151], v[204:207], v[16:19]
	v_mfma_f32_16x16x32_bf16 v[12:15], v[152:155], v[200:203], v[12:15]
	v_mfma_f32_16x16x32_bf16 v[12:15], v[156:159], v[204:207], v[12:15]
	v_mfma_f32_16x16x32_bf16 v[28:31], v[152:155], v[192:195], v[28:31]
	v_mfma_f32_16x16x32_bf16 v[28:31], v[156:159], v[196:199], v[28:31]
	v_mfma_f32_16x16x32_bf16 v[44:47], v[152:155], v[184:187], v[44:47]
	v_mfma_f32_16x16x32_bf16 v[44:47], v[156:159], v[188:191], v[44:47]
	v_mfma_f32_16x16x32_bf16 v[60:63], v[152:155], v[176:179], v[60:63]
	v_mfma_f32_16x16x32_bf16 v[60:63], v[156:159], v[180:183], v[60:63]

.Lt13b_1:
	s_setprio 0
	s_barrier
	v_add_u32_e32 v156, s45, v142
	v_add_u32_e32 v172, s74, v142
	ds_read_b128 v[144:147], v156
	ds_read_b128 v[148:151], v156 offset:1024
	ds_read_b128 v[152:155], v156 offset:2048
	ds_read_b128 v[156:159], v156 offset:3072
	ds_read_b128 v[160:163], v172
	ds_read_b128 v[164:167], v172 offset:1024
	ds_read_b128 v[168:171], v172 offset:2048
	ds_read_b128 v[172:175], v172 offset:3072
	s_add_u32 s10, s10, 0x80000
	s_addc_u32 s11, s11, 0
	s_mov_b32 m0, s22
	v_lshl_add_u64 v[220:221], s[10:11], 0, v[132:133]
	ds_read_b128 v[176:179], v143 offset:32768
	ds_read_b128 v[180:183], v143 offset:33792
	ds_read_b128 v[184:187], v143 offset:34816
	ds_read_b128 v[188:191], v143 offset:35840
	ds_read_b128 v[192:195], v143 offset:36864
	ds_read_b128 v[196:199], v143 offset:37888
	ds_read_b128 v[200:203], v143 offset:38912
	ds_read_b128 v[204:207], v143 offset:39936
	global_load_lds_dwordx4 v[220:221], off
	v_lshl_add_u64 v[220:221], s[10:11], 0, v[134:135]
	s_mov_b32 m0, s23
	s_nop 0
	global_load_lds_dwordx4 v[220:221], off
	s_waitcnt vmcnt(8)
	s_waitcnt lgkmcnt(0)
	s_setprio 1
	s_barrier
	s_cmp_lg_u32 s101, 0
	s_cbranch_scc1 .Lt13a_2
	v_mfma_f32_16x16x32_bf16 v[128:131], v[144:147], v[176:179], v[128:131]
	v_mfma_f32_16x16x32_bf16 v[128:131], v[148:151], v[180:183], v[128:131]
	v_mfma_f32_16x16x32_bf16 v[112:115], v[144:147], v[184:187], v[112:115]
	v_mfma_f32_16x16x32_bf16 v[112:115], v[148:151], v[188:191], v[112:115]
	v_mfma_f32_16x16x32_bf16 v[96:99], v[144:147], v[192:195], v[96:99]
	v_mfma_f32_16x16x32_bf16 v[96:99], v[148:151], v[196:199], v[96:99]
	v_mfma_f32_16x16x32_bf16 v[80:83], v[144:147], v[200:203], v[80:83]
	v_mfma_f32_16x16x32_bf16 v[80:83], v[148:151], v[204:207], v[80:83]
	v_mfma_f32_16x16x32_bf16 v[76:79], v[152:155], v[200:203], v[76:79]
	v_mfma_f32_16x16x32_bf16 v[76:79], v[156:159], v[204:207], v[76:79]
	v_mfma_f32_16x16x32_bf16 v[92:95], v[152:155], v[192:195], v[92:95]
	v_mfma_f32_16x16x32_bf16 v[92:95], v[156:159], v[196:199], v[92:95]
	v_mfma_f32_16x16x32_bf16 v[108:111], v[152:155], v[184:187], v[108:111]
	v_mfma_f32_16x16x32_bf16 v[108:111], v[156:159], v[188:191], v[108:111]
	v_mfma_f32_16x16x32_bf16 v[124:127], v[152:155], v[176:179], v[124:127]
	v_mfma_f32_16x16x32_bf16 v[124:127], v[156:159], v[180:183], v[124:127]

.Lt13b_2:
	s_setprio 0
	s_barrier
	s_mov_b32 m0, s24
	v_lshl_add_u64 v[208:209], v[208:209], 0, s[64:65]
	s_add_u32 s8, s8, 0x80080
	ds_read_b128 v[176:179], v143 offset:49152
	ds_read_b128 v[180:183], v143 offset:50176
	ds_read_b128 v[184:187], v143 offset:51200
	ds_read_b128 v[188:191], v143 offset:52224
	ds_read_b128 v[192:195], v143 offset:53248
	ds_read_b128 v[196:199], v143 offset:54272
	ds_read_b128 v[200:203], v143 offset:55296
	ds_read_b128 v[204:207], v143 offset:56320
	global_load_lds_dwordx4 v[208:209], off
	v_lshl_add_u64 v[208:209], v[210:211], 0, s[64:65]
	s_mov_b32 m0, s25
	s_addc_u32 s9, s9, 0
	global_load_lds_dwordx4 v[208:209], off
	v_lshl_add_u64 v[208:209], s[8:9], 0, v[2:3]
	s_mov_b32 m0, s34
	s_nop 0
	global_load_lds_dwordx4 v[208:209], off
	v_lshl_add_u64 v[208:209], s[8:9], 0, v[136:137]
	s_mov_b32 m0, s35
	s_nop 0
	global_load_lds_dwordx4 v[208:209], off
	v_lshl_add_u64 v[208:209], v[216:217], 0, s[64:65]
	s_mov_b32 m0, s26
	s_nop 0
	global_load_lds_dwordx4 v[208:209], off
	v_lshl_add_u64 v[208:209], v[218:219], 0, s[64:65]
	s_mov_b32 m0, s27
	s_nop 0
	global_load_lds_dwordx4 v[208:209], off
	s_waitcnt vmcnt(8)
	s_waitcnt lgkmcnt(0)
	s_setprio 1
	s_barrier
	s_cmp_lg_u32 s101, 0
	s_cbranch_scc1 .Lt13a_3
	v_mfma_f32_16x16x32_bf16 v[64:67], v[144:147], v[176:179], v[64:67]
	v_mfma_f32_16x16x32_bf16 v[64:67], v[148:151], v[180:183], v[64:67]
	v_mfma_f32_16x16x32_bf16 v[48:51], v[144:147], v[184:187], v[48:51]
	v_mfma_f32_16x16x32_bf16 v[48:51], v[148:151], v[188:191], v[48:51]
	v_mfma_f32_16x16x32_bf16 v[32:35], v[144:147], v[192:195], v[32:35]
	v_mfma_f32_16x16x32_bf16 v[32:35], v[148:151], v[196:199], v[32:35]
	v_mfma_f32_16x16x32_bf16 v[16:19], v[144:147], v[200:203], v[16:19]
	v_mfma_f32_16x16x32_bf16 v[16:19], v[148:151], v[204:207], v[16:19]
	v_mfma_f32_16x16x32_bf16 v[12:15], v[152:155], v[200:203], v[12:15]
	v_mfma_f32_16x16x32_bf16 v[12:15], v[156:159], v[204:207], v[12:15]
	v_mfma_f32_16x16x32_bf16 v[28:31], v[152:155], v[192:195], v[28:31]
	v_mfma_f32_16x16x32_bf16 v[28:31], v[156:159], v[196:199], v[28:31]
	v_mfma_f32_16x16x32_bf16 v[44:47], v[152:155], v[184:187], v[44:47]
	v_mfma_f32_16x16x32_bf16 v[44:47], v[156:159], v[188:191], v[44:47]
	v_mfma_f32_16x16x32_bf16 v[60:63], v[152:155], v[176:179], v[60:63]
	v_mfma_f32_16x16x32_bf16 v[60:63], v[156:159], v[180:183], v[60:63]

.LBB0_1876:
	v_add_u32_e32 v2, s83, v144
	ds_read_b128 v[146:149], v2
	ds_read_b128 v[150:153], v2 offset:1024
	ds_read_b128 v[154:157], v2 offset:2048
	ds_read_b128 v[158:161], v2 offset:3072
	v_add_u32_e32 v2, s44, v144
	ds_read_b128 v[162:165], v2
	ds_read_b128 v[166:169], v2 offset:1024
	ds_read_b128 v[170:173], v2 offset:2048
	ds_read_b128 v[174:177], v2 offset:3072
	s_add_i32 s70, s18, 2
	s_add_u32 s71, s42, 0x80
	s_addc_u32 s19, s43, 0
	s_cmp_eq_u32 s57, s18
	s_cselect_b32 s18, s34, s71
	s_cselect_b32 s19, s35, s19
	s_cselect_b32 s77, s25, s69
	s_cselect_b32 s76, s24, s68
	v_lshl_add_u64 v[210:211], s[42:43], 0, v[140:141]
	s_add_i32 m0, s23, 0xc000
	ds_read_b128 v[178:181], v145
	ds_read_b128 v[182:185], v145 offset:1024
	ds_read_b128 v[186:189], v145 offset:2048
	ds_read_b128 v[190:193], v145 offset:3072
	ds_read_b128 v[194:197], v145 offset:4096
	ds_read_b128 v[198:201], v145 offset:5120
	ds_read_b128 v[202:205], v145 offset:6144
	ds_read_b128 v[206:209], v145 offset:7168
	global_load_lds_dwordx4 v[210:211], off
	v_lshl_add_u64 v[210:211], s[42:43], 0, v[142:143]
	s_add_i32 m0, s23, 0xe000
	s_nop 0
	global_load_lds_dwordx4 v[210:211], off
	s_waitcnt vmcnt(8)
	s_waitcnt lgkmcnt(0)
	s_setprio 1
	s_barrier
	v_mfma_f32_16x16x32_bf16 v[120:123], v[146:149], v[178:181], v[120:123]
	v_mfma_f32_16x16x32_bf16 v[120:123], v[150:153], v[182:185], v[120:123]
	v_mfma_f32_16x16x32_bf16 v[112:115], v[146:149], v[186:189], v[112:115]
	v_mfma_f32_16x16x32_bf16 v[112:115], v[150:153], v[190:193], v[112:115]
	v_mfma_f32_16x16x32_bf16 v[96:99], v[146:149], v[194:197], v[96:99]
	v_mfma_f32_16x16x32_bf16 v[96:99], v[150:153], v[198:201], v[96:99]
	v_mfma_f32_16x16x32_bf16 v[80:83], v[146:149], v[202:205], v[80:83]
	v_mfma_f32_16x16x32_bf16 v[80:83], v[150:153], v[206:209], v[80:83]
	v_mfma_f32_16x16x32_bf16 v[76:79], v[154:157], v[202:205], v[76:79]
	v_mfma_f32_16x16x32_bf16 v[76:79], v[158:161], v[206:209], v[76:79]
	v_mfma_f32_16x16x32_bf16 v[92:95], v[154:157], v[194:197], v[92:95]
	v_mfma_f32_16x16x32_bf16 v[92:95], v[158:161], v[198:201], v[92:95]
	v_mfma_f32_16x16x32_bf16 v[108:111], v[154:157], v[186:189], v[108:111]
	v_mfma_f32_16x16x32_bf16 v[108:111], v[158:161], v[190:193], v[108:111]
	v_mfma_f32_16x16x32_bf16 v[128:131], v[154:157], v[178:181], v[128:131]
	v_mfma_f32_16x16x32_bf16 v[128:131], v[158:161], v[182:185], v[128:131]
	s_setprio 0
	s_setprio 1
	v_mfma_f32_16x16x32_bf16 v[124:127], v[162:165], v[178:181], v[124:127]
	v_mfma_f32_16x16x32_bf16 v[124:127], v[166:169], v[182:185], v[124:127]
	v_mfma_f32_16x16x32_bf16 v[104:107], v[162:165], v[186:189], v[104:107]
	v_mfma_f32_16x16x32_bf16 v[104:107], v[166:169], v[190:193], v[104:107]
	v_mfma_f32_16x16x32_bf16 v[88:91], v[162:165], v[194:197], v[88:91]
	v_mfma_f32_16x16x32_bf16 v[88:91], v[166:169], v[198:201], v[88:91]
	v_mfma_f32_16x16x32_bf16 v[72:75], v[162:165], v[202:205], v[72:75]
	v_mfma_f32_16x16x32_bf16 v[72:75], v[166:169], v[206:209], v[72:75]
	v_mfma_f32_16x16x32_bf16 v[68:71], v[170:173], v[202:205], v[68:71]
	v_mfma_f32_16x16x32_bf16 v[68:71], v[174:177], v[206:209], v[68:71]
	v_mfma_f32_16x16x32_bf16 v[84:87], v[170:173], v[194:197], v[84:87]
	v_mfma_f32_16x16x32_bf16 v[84:87], v[174:177], v[198:201], v[84:87]
	v_mfma_f32_16x16x32_bf16 v[100:103], v[170:173], v[186:189], v[100:103]
	v_mfma_f32_16x16x32_bf16 v[100:103], v[174:177], v[190:193], v[100:103]
	v_mfma_f32_16x16x32_bf16 v[116:119], v[170:173], v[178:181], v[116:119]
	v_mfma_f32_16x16x32_bf16 v[116:119], v[174:177], v[182:185], v[116:119]
	s_setprio 0
	s_barrier
	s_mov_b32 m0, s16
	v_lshl_add_u64 v[210:211], s[76:77], 0, v[134:135]
	v_lshl_add_u64 v[216:217], s[76:77], 0, v[138:139]
	s_add_u32 s76, s76, s4
	ds_read_b128 v[178:181], v145 offset:16384
	ds_read_b128 v[182:185], v145 offset:17408
	ds_read_b128 v[186:189], v145 offset:18432
	ds_read_b128 v[190:193], v145 offset:19456
	ds_read_b128 v[194:197], v145 offset:20480
	ds_read_b128 v[198:201], v145 offset:21504
	ds_read_b128 v[202:205], v145 offset:22528
	ds_read_b128 v[206:209], v145 offset:23552
	global_load_lds_dwordx4 v[210:211], off
	s_mov_b32 m0, s20
	s_addc_u32 s77, s77, s5
	global_load_lds_dwordx4 v[216:217], off
	v_lshl_add_u64 v[218:219], s[76:77], 0, v[134:135]
	s_mov_b32 m0, s21
	v_lshl_add_u64 v[220:221], s[76:77], 0, v[138:139]
	global_load_lds_dwordx4 v[218:219], off
	s_mov_b32 m0, s22
	v_lshl_add_u64 v[222:223], s[18:19], 0, v[132:133]
	global_load_lds_dwordx4 v[220:221], off
	s_mov_b32 m0, s23
	v_lshl_add_u64 v[224:225], s[18:19], 0, v[136:137]
	global_load_lds_dwordx4 v[222:223], off
	s_mov_b32 m0, s26
	s_nop 0
	global_load_lds_dwordx4 v[224:225], off
	s_waitcnt vmcnt(8)
	s_waitcnt lgkmcnt(0)
	s_setprio 1
	s_barrier
	v_mfma_f32_16x16x32_bf16 v[64:67], v[146:149], v[178:181], v[64:67]
	v_mfma_f32_16x16x32_bf16 v[64:67], v[150:153], v[182:185], v[64:67]
	v_mfma_f32_16x16x32_bf16 v[48:51], v[146:149], v[186:189], v[48:51]
	v_mfma_f32_16x16x32_bf16 v[48:51], v[150:153], v[190:193], v[48:51]
	v_mfma_f32_16x16x32_bf16 v[32:35], v[146:149], v[194:197], v[32:35]
	v_mfma_f32_16x16x32_bf16 v[32:35], v[150:153], v[198:201], v[32:35]
	v_mfma_f32_16x16x32_bf16 v[16:19], v[146:149], v[202:205], v[16:19]
	v_mfma_f32_16x16x32_bf16 v[16:19], v[150:153], v[206:209], v[16:19]
	v_mfma_f32_16x16x32_bf16 v[12:15], v[154:157], v[202:205], v[12:15]
	v_mfma_f32_16x16x32_bf16 v[12:15], v[158:161], v[206:209], v[12:15]
	v_mfma_f32_16x16x32_bf16 v[28:31], v[154:157], v[194:197], v[28:31]
	v_mfma_f32_16x16x32_bf16 v[28:31], v[158:161], v[198:201], v[28:31]
	v_mfma_f32_16x16x32_bf16 v[44:47], v[154:157], v[186:189], v[44:47]
	v_mfma_f32_16x16x32_bf16 v[44:47], v[158:161], v[190:193], v[44:47]
	v_mfma_f32_16x16x32_bf16 v[60:63], v[154:157], v[178:181], v[60:63]
	v_mfma_f32_16x16x32_bf16 v[60:63], v[158:161], v[182:185], v[60:63]
	s_setprio 0
	s_setprio 1
	v_mfma_f32_16x16x32_bf16 v[56:59], v[162:165], v[178:181], v[56:59]
	v_mfma_f32_16x16x32_bf16 v[56:59], v[166:169], v[182:185], v[56:59]
	v_mfma_f32_16x16x32_bf16 v[40:43], v[162:165], v[186:189], v[40:43]
	v_mfma_f32_16x16x32_bf16 v[40:43], v[166:169], v[190:193], v[40:43]
	v_mfma_f32_16x16x32_bf16 v[24:27], v[162:165], v[194:197], v[24:27]
	v_mfma_f32_16x16x32_bf16 v[24:27], v[166:169], v[198:201], v[24:27]
	v_mfma_f32_16x16x32_bf16 v[8:11], v[162:165], v[202:205], v[8:11]
	v_mfma_f32_16x16x32_bf16 v[8:11], v[166:169], v[206:209], v[8:11]
	v_mfma_f32_16x16x32_bf16 v[4:7], v[170:173], v[202:205], v[4:7]
	v_mfma_f32_16x16x32_bf16 v[4:7], v[174:177], v[206:209], v[4:7]
	v_mfma_f32_16x16x32_bf16 v[20:23], v[170:173], v[194:197], v[20:23]
	v_mfma_f32_16x16x32_bf16 v[20:23], v[174:177], v[198:201], v[20:23]
	v_mfma_f32_16x16x32_bf16 v[36:39], v[170:173], v[186:189], v[36:39]
	v_mfma_f32_16x16x32_bf16 v[36:39], v[174:177], v[190:193], v[36:39]
	v_mfma_f32_16x16x32_bf16 v[52:55], v[170:173], v[178:181], v[52:55]
	v_mfma_f32_16x16x32_bf16 v[52:55], v[174:177], v[182:185], v[52:55]
	s_setprio 0
	s_barrier
	v_add_u32_e32 v2, s45, v144
	ds_read_b128 v[146:149], v2
	ds_read_b128 v[150:153], v2 offset:1024
	ds_read_b128 v[154:157], v2 offset:2048
	ds_read_b128 v[158:161], v2 offset:3072
	v_add_u32_e32 v2, s74, v144
	ds_read_b128 v[162:165], v2
	ds_read_b128 v[166:169], v2 offset:1024
	ds_read_b128 v[170:173], v2 offset:2048
	ds_read_b128 v[174:177], v2 offset:3072
	s_add_u32 s18, s18, s4
	s_addc_u32 s19, s19, s5
	s_mov_b32 m0, s27
	v_lshl_add_u64 v[226:227], s[18:19], 0, v[132:133]
	ds_read_b128 v[178:181], v145 offset:32768
	ds_read_b128 v[182:185], v145 offset:33792
	ds_read_b128 v[186:189], v145 offset:34816
	ds_read_b128 v[190:193], v145 offset:35840
	ds_read_b128 v[194:197], v145 offset:36864
	ds_read_b128 v[198:201], v145 offset:37888
	ds_read_b128 v[202:205], v145 offset:38912
	ds_read_b128 v[206:209], v145 offset:39936
	global_load_lds_dwordx4 v[226:227], off
	v_lshl_add_u64 v[226:227], s[18:19], 0, v[136:137]
	s_mov_b32 m0, s37
	s_nop 0
	global_load_lds_dwordx4 v[226:227], off
	s_waitcnt vmcnt(8)
	s_waitcnt lgkmcnt(0)
	s_setprio 1
	s_barrier
	v_mfma_f32_16x16x32_bf16 v[120:123], v[146:149], v[178:181], v[120:123]
	v_mfma_f32_16x16x32_bf16 v[120:123], v[150:153], v[182:185], v[120:123]
	v_mfma_f32_16x16x32_bf16 v[112:115], v[146:149], v[186:189], v[112:115]
	v_mfma_f32_16x16x32_bf16 v[112:115], v[150:153], v[190:193], v[112:115]
	v_mfma_f32_16x16x32_bf16 v[96:99], v[146:149], v[194:197], v[96:99]
	v_mfma_f32_16x16x32_bf16 v[96:99], v[150:153], v[198:201], v[96:99]
	v_mfma_f32_16x16x32_bf16 v[80:83], v[146:149], v[202:205], v[80:83]
	v_mfma_f32_16x16x32_bf16 v[80:83], v[150:153], v[206:209], v[80:83]
	v_mfma_f32_16x16x32_bf16 v[76:79], v[154:157], v[202:205], v[76:79]
	v_mfma_f32_16x16x32_bf16 v[76:79], v[158:161], v[206:209], v[76:79]
	v_mfma_f32_16x16x32_bf16 v[92:95], v[154:157], v[194:197], v[92:95]
	v_mfma_f32_16x16x32_bf16 v[92:95], v[158:161], v[198:201], v[92:95]
	v_mfma_f32_16x16x32_bf16 v[108:111], v[154:157], v[186:189], v[108:111]
	v_mfma_f32_16x16x32_bf16 v[108:111], v[158:161], v[190:193], v[108:111]
	v_mfma_f32_16x16x32_bf16 v[128:131], v[154:157], v[178:181], v[128:131]
	v_mfma_f32_16x16x32_bf16 v[128:131], v[158:161], v[182:185], v[128:131]
	s_setprio 0
	s_setprio 1
	v_mfma_f32_16x16x32_bf16 v[124:127], v[162:165], v[178:181], v[124:127]
	v_mfma_f32_16x16x32_bf16 v[124:127], v[166:169], v[182:185], v[124:127]
	v_mfma_f32_16x16x32_bf16 v[104:107], v[162:165], v[186:189], v[104:107]
	v_mfma_f32_16x16x32_bf16 v[104:107], v[166:169], v[190:193], v[104:107]
	v_mfma_f32_16x16x32_bf16 v[88:91], v[162:165], v[194:197], v[88:91]
	v_mfma_f32_16x16x32_bf16 v[88:91], v[166:169], v[198:201], v[88:91]
	v_mfma_f32_16x16x32_bf16 v[72:75], v[162:165], v[202:205], v[72:75]
	v_mfma_f32_16x16x32_bf16 v[72:75], v[166:169], v[206:209], v[72:75]
	v_mfma_f32_16x16x32_bf16 v[68:71], v[170:173], v[202:205], v[68:71]
	v_mfma_f32_16x16x32_bf16 v[68:71], v[174:177], v[206:209], v[68:71]
	v_mfma_f32_16x16x32_bf16 v[84:87], v[170:173], v[194:197], v[84:87]
	v_mfma_f32_16x16x32_bf16 v[84:87], v[174:177], v[198:201], v[84:87]
	v_mfma_f32_16x16x32_bf16 v[100:103], v[170:173], v[186:189], v[100:103]
	v_mfma_f32_16x16x32_bf16 v[100:103], v[174:177], v[190:193], v[100:103]
	v_mfma_f32_16x16x32_bf16 v[116:119], v[170:173], v[178:181], v[116:119]
	v_mfma_f32_16x16x32_bf16 v[116:119], v[174:177], v[182:185], v[116:119]
	s_setprio 0
	s_barrier
	s_mov_b32 m0, s49
	v_lshl_add_u64 v[210:211], v[210:211], 0, s[64:65]
	ds_read_b128 v[178:181], v145 offset:49152
	ds_read_b128 v[182:185], v145 offset:50176
	ds_read_b128 v[186:189], v145 offset:51200
	ds_read_b128 v[190:193], v145 offset:52224
	ds_read_b128 v[194:197], v145 offset:53248
	ds_read_b128 v[198:201], v145 offset:54272
	ds_read_b128 v[202:205], v145 offset:55296
	ds_read_b128 v[206:209], v145 offset:56320
	global_load_lds_dwordx4 v[210:211], off
	v_lshl_add_u64 v[210:211], v[216:217], 0, s[64:65]
	s_mov_b32 m0, s50
	s_nop 0
	global_load_lds_dwordx4 v[210:211], off
	v_lshl_add_u64 v[210:211], v[218:219], 0, s[64:65]
	s_mov_b32 m0, s53
	s_nop 0
	global_load_lds_dwordx4 v[210:211], off
	v_lshl_add_u64 v[210:211], v[220:221], 0, s[64:65]
	s_mov_b32 m0, s56
	s_nop 0
	global_load_lds_dwordx4 v[210:211], off
	v_lshl_add_u64 v[210:211], v[222:223], 0, s[64:65]
	s_mov_b32 m0, s51
	s_nop 0
	global_load_lds_dwordx4 v[210:211], off
	v_lshl_add_u64 v[210:211], v[224:225], 0, s[64:65]
	s_mov_b32 m0, s52
	s_nop 0
	global_load_lds_dwordx4 v[210:211], off
	s_waitcnt vmcnt(8)
	s_waitcnt lgkmcnt(0)
	s_setprio 1
	s_barrier
	v_mfma_f32_16x16x32_bf16 v[64:67], v[146:149], v[178:181], v[64:67]
	v_mfma_f32_16x16x32_bf16 v[64:67], v[150:153], v[182:185], v[64:67]
	v_mfma_f32_16x16x32_bf16 v[48:51], v[146:149], v[186:189], v[48:51]
	v_mfma_f32_16x16x32_bf16 v[48:51], v[150:153], v[190:193], v[48:51]
	v_mfma_f32_16x16x32_bf16 v[32:35], v[146:149], v[194:197], v[32:35]
	v_mfma_f32_16x16x32_bf16 v[32:35], v[150:153], v[198:201], v[32:35]
	v_mfma_f32_16x16x32_bf16 v[16:19], v[146:149], v[202:205], v[16:19]
	v_mfma_f32_16x16x32_bf16 v[16:19], v[150:153], v[206:209], v[16:19]
	v_mfma_f32_16x16x32_bf16 v[12:15], v[154:157], v[202:205], v[12:15]
	v_mfma_f32_16x16x32_bf16 v[12:15], v[158:161], v[206:209], v[12:15]
	v_mfma_f32_16x16x32_bf16 v[28:31], v[154:157], v[194:197], v[28:31]
	v_mfma_f32_16x16x32_bf16 v[28:31], v[158:161], v[198:201], v[28:31]
	v_mfma_f32_16x16x32_bf16 v[44:47], v[154:157], v[186:189], v[44:47]
	v_mfma_f32_16x16x32_bf16 v[44:47], v[158:161], v[190:193], v[44:47]
	v_mfma_f32_16x16x32_bf16 v[60:63], v[154:157], v[178:181], v[60:63]
	v_mfma_f32_16x16x32_bf16 v[60:63], v[158:161], v[182:185], v[60:63]
	s_setprio 0
	s_setprio 1
	v_mfma_f32_16x16x32_bf16 v[56:59], v[162:165], v[178:181], v[56:59]
	v_mfma_f32_16x16x32_bf16 v[56:59], v[166:169], v[182:185], v[56:59]
	v_mfma_f32_16x16x32_bf16 v[40:43], v[162:165], v[186:189], v[40:43]
	v_mfma_f32_16x16x32_bf16 v[40:43], v[166:169], v[190:193], v[40:43]
	v_mfma_f32_16x16x32_bf16 v[24:27], v[162:165], v[194:197], v[24:27]
	v_mfma_f32_16x16x32_bf16 v[24:27], v[166:169], v[198:201], v[24:27]
	v_mfma_f32_16x16x32_bf16 v[8:11], v[162:165], v[202:205], v[8:11]
	v_mfma_f32_16x16x32_bf16 v[8:11], v[166:169], v[206:209], v[8:11]
	v_mfma_f32_16x16x32_bf16 v[4:7], v[170:173], v[202:205], v[4:7]
	v_mfma_f32_16x16x32_bf16 v[4:7], v[174:177], v[206:209], v[4:7]
	v_mfma_f32_16x16x32_bf16 v[20:23], v[170:173], v[194:197], v[20:23]
	v_mfma_f32_16x16x32_bf16 v[20:23], v[174:177], v[198:201], v[20:23]
	v_mfma_f32_16x16x32_bf16 v[36:39], v[170:173], v[186:189], v[36:39]
	v_mfma_f32_16x16x32_bf16 v[36:39], v[174:177], v[190:193], v[36:39]
	v_mfma_f32_16x16x32_bf16 v[52:55], v[170:173], v[178:181], v[52:55]
	v_mfma_f32_16x16x32_bf16 v[52:55], v[174:177], v[182:185], v[52:55]
	s_setprio 0
	s_barrier
	s_add_u32 s42, s42, 0x100
	s_addc_u32 s43, s43, 0
	s_add_u32 s68, s68, 0x100
	s_addc_u32 s69, s69, 0
	s_cmp_ge_i32 s70, s46
	s_mov_b32 s18, s70
	s_cbranch_scc0 .LBB0_1876

.LBB0_1891:
	v_add_u32_e32 v2, s83, v189
	ds_read_b128 v[28:31], v2
	ds_read_b128 v[32:35], v2 offset:16
	ds_read_b128 v[20:23], v2 offset:2048
	ds_read_b128 v[24:27], v2 offset:2064
	v_add_u32_e32 v2, s44, v189
	ds_read_b128 v[12:15], v2
	ds_read_b128 v[16:19], v2 offset:16
	ds_read_b128 v[4:7], v2 offset:2048
	ds_read_b128 v[8:11], v2 offset:2064
	s_add_u32 s10, s8, 0xfffc0080
	s_addc_u32 s11, s9, -1
	s_cmp_eq_u32 s25, 12
	s_cselect_b32 s13, s3, s11
	s_cselect_b32 s12, s14, s10
	s_cselect_b32 s11, s15, s24
	s_cselect_b32 s10, s18, s19
	v_lshl_add_u64 v[208:209], s[8:9], 0, v[172:173]
	s_add_i32 m0, s16, 0xc000
	ds_read_b128 v[176:179], v191
	ds_read_b128 v[180:183], v191 offset:16
	ds_read_b128 v[192:195], v191 offset:2048
	ds_read_b128 v[196:199], v191 offset:2064
	ds_read_b128 v[200:203], v191 offset:4096
	ds_read_b128 v[204:207], v191 offset:4112
	ds_read_b128 v[216:219], v191 offset:6144
	ds_read_b128 v[220:223], v191 offset:6160
	global_load_lds_dwordx4 v[208:209], off
	v_lshl_add_u64 v[208:209], s[8:9], 0, v[174:175]
	s_add_i32 m0, s16, 0xe000
	s_nop 0
	global_load_lds_dwordx4 v[208:209], off
	s_waitcnt vmcnt(8)
	s_waitcnt lgkmcnt(0)
	s_setprio 1
	s_barrier
	v_mfma_scale_f32_16x16x128_f8f6f4 v[160:163], v[28:35], v[176:183], v[160:163], v187, v185 op_sel_hi:[0,0,0]
	v_mfma_scale_f32_16x16x128_f8f6f4 v[156:159], v[20:27], v[176:183], v[156:159], v187, v185 op_sel_hi:[0,0,0]
	v_mfma_scale_f32_16x16x128_f8f6f4 v[144:147], v[28:35], v[192:199], v[144:147], v187, v185 op_sel_hi:[0,0,0]
	v_mfma_scale_f32_16x16x128_f8f6f4 v[140:143], v[20:27], v[192:199], v[140:143], v187, v185 op_sel_hi:[0,0,0]
	v_mfma_scale_f32_16x16x128_f8f6f4 v[128:131], v[28:35], v[200:207], v[128:131], v187, v185 op_sel_hi:[0,0,0]
	v_mfma_scale_f32_16x16x128_f8f6f4 v[124:127], v[20:27], v[200:207], v[124:127], v187, v185 op_sel_hi:[0,0,0]
	v_mfma_scale_f32_16x16x128_f8f6f4 v[112:115], v[28:35], v[216:223], v[112:115], v187, v185 op_sel_hi:[0,0,0]
	v_mfma_scale_f32_16x16x128_f8f6f4 v[108:111], v[20:27], v[216:223], v[108:111], v187, v185 op_sel_hi:[0,0,0]
	s_setprio 0
	s_setprio 1
	v_mfma_scale_f32_16x16x128_f8f6f4 v[152:155], v[12:19], v[176:183], v[152:155], v187, v185 op_sel_hi:[0,0,0]
	v_mfma_scale_f32_16x16x128_f8f6f4 v[148:151], v[4:11], v[176:183], v[148:151], v187, v185 op_sel_hi:[0,0,0]
	v_mfma_scale_f32_16x16x128_f8f6f4 v[136:139], v[12:19], v[192:199], v[136:139], v187, v185 op_sel_hi:[0,0,0]
	v_mfma_scale_f32_16x16x128_f8f6f4 v[132:135], v[4:11], v[192:199], v[132:135], v187, v185 op_sel_hi:[0,0,0]
	v_mfma_scale_f32_16x16x128_f8f6f4 v[120:123], v[12:19], v[200:207], v[120:123], v187, v185 op_sel_hi:[0,0,0]
	v_mfma_scale_f32_16x16x128_f8f6f4 v[116:119], v[4:11], v[200:207], v[116:119], v187, v185 op_sel_hi:[0,0,0]
	v_mfma_scale_f32_16x16x128_f8f6f4 v[104:107], v[12:19], v[216:223], v[104:107], v187, v185 op_sel_hi:[0,0,0]
	v_mfma_scale_f32_16x16x128_f8f6f4 v[100:103], v[4:11], v[216:223], v[100:103], v187, v185 op_sel_hi:[0,0,0]
	s_setprio 0
	s_barrier
	s_mov_b32 m0, s22
	v_lshl_add_u64 v[176:177], s[10:11], 0, v[166:167]
	s_add_u32 s56, s10, 0x40000
	ds_read_b128 v[192:195], v191 offset:16384
	ds_read_b128 v[196:199], v191 offset:16400
	ds_read_b128 v[200:203], v191 offset:18432
	ds_read_b128 v[204:207], v191 offset:18448
	ds_read_b128 v[216:219], v191 offset:20480
	ds_read_b128 v[220:223], v191 offset:20496
	ds_read_b128 v[224:227], v191 offset:22528
	ds_read_b128 v[228:231], v191 offset:22544
	global_load_lds_dwordx4 v[176:177], off
	v_lshl_add_u64 v[178:179], s[10:11], 0, v[170:171]
	s_mov_b32 m0, s23
	s_addc_u32 s57, s11, 0
	global_load_lds_dwordx4 v[178:179], off
	v_lshl_add_u64 v[180:181], s[56:57], 0, v[166:167]
	s_mov_b32 m0, s75
	v_lshl_add_u64 v[182:183], s[12:13], 0, v[168:169]
	global_load_lds_dwordx4 v[180:181], off
	v_lshl_add_u64 v[180:181], s[56:57], 0, v[170:171]
	s_mov_b32 m0, s37
	s_nop 0
	global_load_lds_dwordx4 v[180:181], off
	v_lshl_add_u64 v[180:181], s[12:13], 0, v[164:165]
	s_mov_b32 m0, s16
	s_nop 0
	global_load_lds_dwordx4 v[180:181], off
	s_mov_b32 m0, s73
	s_nop 0
	global_load_lds_dwordx4 v[182:183], off
	s_waitcnt vmcnt(8)
	s_waitcnt lgkmcnt(0)
	s_setprio 1
	s_barrier
	v_mfma_scale_f32_16x16x128_f8f6f4 v[96:99], v[28:35], v[192:199], v[96:99], v187, v185 op_sel_hi:[0,0,0]
	v_mfma_scale_f32_16x16x128_f8f6f4 v[92:95], v[20:27], v[192:199], v[92:95], v187, v185 op_sel_hi:[0,0,0]
	v_mfma_scale_f32_16x16x128_f8f6f4 v[80:83], v[28:35], v[200:207], v[80:83], v187, v185 op_sel_hi:[0,0,0]
	v_mfma_scale_f32_16x16x128_f8f6f4 v[76:79], v[20:27], v[200:207], v[76:79], v187, v185 op_sel_hi:[0,0,0]
	v_mfma_scale_f32_16x16x128_f8f6f4 v[64:67], v[28:35], v[216:223], v[64:67], v187, v185 op_sel_hi:[0,0,0]
	v_mfma_scale_f32_16x16x128_f8f6f4 v[60:63], v[20:27], v[216:223], v[60:63], v187, v185 op_sel_hi:[0,0,0]
	v_mfma_scale_f32_16x16x128_f8f6f4 v[48:51], v[28:35], v[224:231], v[48:51], v187, v185 op_sel_hi:[0,0,0]
	v_mfma_scale_f32_16x16x128_f8f6f4 v[44:47], v[20:27], v[224:231], v[44:47], v187, v185 op_sel_hi:[0,0,0]
	s_setprio 0
	s_setprio 1
	v_mfma_scale_f32_16x16x128_f8f6f4 v[88:91], v[12:19], v[192:199], v[88:91], v187, v185 op_sel_hi:[0,0,0]
	v_mfma_scale_f32_16x16x128_f8f6f4 v[84:87], v[4:11], v[192:199], v[84:87], v187, v185 op_sel_hi:[0,0,0]
	v_mfma_scale_f32_16x16x128_f8f6f4 v[72:75], v[12:19], v[200:207], v[72:75], v187, v185 op_sel_hi:[0,0,0]
	v_mfma_scale_f32_16x16x128_f8f6f4 v[68:71], v[4:11], v[200:207], v[68:71], v187, v185 op_sel_hi:[0,0,0]
	v_mfma_scale_f32_16x16x128_f8f6f4 v[56:59], v[12:19], v[216:223], v[56:59], v187, v185 op_sel_hi:[0,0,0]
	v_mfma_scale_f32_16x16x128_f8f6f4 v[52:55], v[4:11], v[216:223], v[52:55], v187, v185 op_sel_hi:[0,0,0]
	v_mfma_scale_f32_16x16x128_f8f6f4 v[40:43], v[12:19], v[224:231], v[40:43], v187, v185 op_sel_hi:[0,0,0]
	v_mfma_scale_f32_16x16x128_f8f6f4 v[36:39], v[4:11], v[224:231], v[36:39], v187, v185 op_sel_hi:[0,0,0]
	s_setprio 0
	s_barrier
	v_add_u32_e32 v2, s45, v189
	ds_read_b128 v[28:31], v2
	ds_read_b128 v[32:35], v2 offset:16
	ds_read_b128 v[20:23], v2 offset:2048
	ds_read_b128 v[24:27], v2 offset:2064
	v_add_u32_e32 v2, s74, v189
	ds_read_b128 v[12:15], v2
	ds_read_b128 v[16:19], v2 offset:16
	ds_read_b128 v[4:7], v2 offset:2048
	ds_read_b128 v[8:11], v2 offset:2064
	s_add_u32 s12, s12, 0x40000
	s_addc_u32 s13, s13, 0
	s_mov_b32 m0, s82
	v_lshl_add_u64 v[208:209], s[12:13], 0, v[164:165]
	ds_read_b128 v[192:195], v191 offset:32768
	ds_read_b128 v[196:199], v191 offset:32784
	ds_read_b128 v[200:203], v191 offset:34816
	ds_read_b128 v[204:207], v191 offset:34832
	ds_read_b128 v[216:219], v191 offset:36864
	ds_read_b128 v[220:223], v191 offset:36880
	ds_read_b128 v[224:227], v191 offset:38912
	ds_read_b128 v[228:231], v191 offset:38928
	global_load_lds_dwordx4 v[208:209], off
	v_lshl_add_u64 v[208:209], s[12:13], 0, v[168:169]
	s_mov_b32 m0, s40
	s_nop 0
	global_load_lds_dwordx4 v[208:209], off
	s_waitcnt vmcnt(8)
	s_waitcnt lgkmcnt(0)
	s_setprio 1
	s_barrier
	v_mfma_scale_f32_16x16x128_f8f6f4 v[160:163], v[28:35], v[192:199], v[160:163], v187, v185 op_sel_hi:[0,0,0]
	v_mfma_scale_f32_16x16x128_f8f6f4 v[156:159], v[20:27], v[192:199], v[156:159], v187, v185 op_sel_hi:[0,0,0]
	v_mfma_scale_f32_16x16x128_f8f6f4 v[144:147], v[28:35], v[200:207], v[144:147], v187, v185 op_sel_hi:[0,0,0]
	v_mfma_scale_f32_16x16x128_f8f6f4 v[140:143], v[20:27], v[200:207], v[140:143], v187, v185 op_sel_hi:[0,0,0]
	v_mfma_scale_f32_16x16x128_f8f6f4 v[128:131], v[28:35], v[216:223], v[128:131], v187, v185 op_sel_hi:[0,0,0]
	v_mfma_scale_f32_16x16x128_f8f6f4 v[124:127], v[20:27], v[216:223], v[124:127], v187, v185 op_sel_hi:[0,0,0]
	v_mfma_scale_f32_16x16x128_f8f6f4 v[112:115], v[28:35], v[224:231], v[112:115], v187, v185 op_sel_hi:[0,0,0]
	v_mfma_scale_f32_16x16x128_f8f6f4 v[108:111], v[20:27], v[224:231], v[108:111], v187, v185 op_sel_hi:[0,0,0]
	s_setprio 0
	s_setprio 1
	v_mfma_scale_f32_16x16x128_f8f6f4 v[152:155], v[12:19], v[192:199], v[152:155], v187, v185 op_sel_hi:[0,0,0]
	v_mfma_scale_f32_16x16x128_f8f6f4 v[148:151], v[4:11], v[192:199], v[148:151], v187, v185 op_sel_hi:[0,0,0]
	v_mfma_scale_f32_16x16x128_f8f6f4 v[136:139], v[12:19], v[200:207], v[136:139], v187, v185 op_sel_hi:[0,0,0]
	v_mfma_scale_f32_16x16x128_f8f6f4 v[132:135], v[4:11], v[200:207], v[132:135], v187, v185 op_sel_hi:[0,0,0]
	v_mfma_scale_f32_16x16x128_f8f6f4 v[120:123], v[12:19], v[216:223], v[120:123], v187, v185 op_sel_hi:[0,0,0]
	v_mfma_scale_f32_16x16x128_f8f6f4 v[116:119], v[4:11], v[216:223], v[116:119], v187, v185 op_sel_hi:[0,0,0]
	v_mfma_scale_f32_16x16x128_f8f6f4 v[104:107], v[12:19], v[224:231], v[104:107], v187, v185 op_sel_hi:[0,0,0]
	v_mfma_scale_f32_16x16x128_f8f6f4 v[100:103], v[4:11], v[224:231], v[100:103], v187, v185 op_sel_hi:[0,0,0]
	s_setprio 0
	s_barrier
	s_mov_b32 m0, s49
	v_lshl_add_u64 v[176:177], v[176:177], 0, s[64:65]
	s_add_u32 s10, s10, 0x40080
	ds_read_b128 v[192:195], v191 offset:49152
	ds_read_b128 v[196:199], v191 offset:49168
	ds_read_b128 v[200:203], v191 offset:51200
	ds_read_b128 v[204:207], v191 offset:51216
	ds_read_b128 v[216:219], v191 offset:53248
	ds_read_b128 v[220:223], v191 offset:53264
	ds_read_b128 v[224:227], v191 offset:55296
	ds_read_b128 v[228:231], v191 offset:55312
	global_load_lds_dwordx4 v[176:177], off
	v_lshl_add_u64 v[176:177], v[178:179], 0, s[64:65]
	s_mov_b32 m0, s84
	s_addc_u32 s11, s11, 0
	global_load_lds_dwordx4 v[176:177], off
	v_lshl_add_u64 v[176:177], s[10:11], 0, v[166:167]
	s_mov_b32 m0, s27
	s_nop 0
	global_load_lds_dwordx4 v[176:177], off
	v_lshl_add_u64 v[176:177], s[10:11], 0, v[170:171]
	s_mov_b32 m0, s48
	s_nop 0
	global_load_lds_dwordx4 v[176:177], off
	v_lshl_add_u64 v[176:177], v[180:181], 0, s[64:65]
	s_mov_b32 m0, s85
	s_nop 0
	global_load_lds_dwordx4 v[176:177], off
	v_lshl_add_u64 v[176:177], v[182:183], 0, s[64:65]
	s_mov_b32 m0, s26
	s_nop 0
	global_load_lds_dwordx4 v[176:177], off
	s_waitcnt vmcnt(8)
	s_waitcnt lgkmcnt(0)
	s_setprio 1
	s_barrier
	v_mfma_scale_f32_16x16x128_f8f6f4 v[96:99], v[28:35], v[192:199], v[96:99], v187, v185 op_sel_hi:[0,0,0]
	v_mfma_scale_f32_16x16x128_f8f6f4 v[92:95], v[20:27], v[192:199], v[92:95], v187, v185 op_sel_hi:[0,0,0]
	v_mfma_scale_f32_16x16x128_f8f6f4 v[80:83], v[28:35], v[200:207], v[80:83], v187, v185 op_sel_hi:[0,0,0]
	v_mfma_scale_f32_16x16x128_f8f6f4 v[76:79], v[20:27], v[200:207], v[76:79], v187, v185 op_sel_hi:[0,0,0]
	v_mfma_scale_f32_16x16x128_f8f6f4 v[64:67], v[28:35], v[216:223], v[64:67], v187, v185 op_sel_hi:[0,0,0]
	v_mfma_scale_f32_16x16x128_f8f6f4 v[60:63], v[20:27], v[216:223], v[60:63], v187, v185 op_sel_hi:[0,0,0]
	v_mfma_scale_f32_16x16x128_f8f6f4 v[48:51], v[28:35], v[224:231], v[48:51], v187, v185 op_sel_hi:[0,0,0]
	v_mfma_scale_f32_16x16x128_f8f6f4 v[44:47], v[20:27], v[224:231], v[44:47], v187, v185 op_sel_hi:[0,0,0]
	s_setprio 0
	s_setprio 1
	v_mfma_scale_f32_16x16x128_f8f6f4 v[88:91], v[12:19], v[192:199], v[88:91], v187, v185 op_sel_hi:[0,0,0]
	v_mfma_scale_f32_16x16x128_f8f6f4 v[84:87], v[4:11], v[192:199], v[84:87], v187, v185 op_sel_hi:[0,0,0]
	v_mfma_scale_f32_16x16x128_f8f6f4 v[72:75], v[12:19], v[200:207], v[72:75], v187, v185 op_sel_hi:[0,0,0]
	v_mfma_scale_f32_16x16x128_f8f6f4 v[68:71], v[4:11], v[200:207], v[68:71], v187, v185 op_sel_hi:[0,0,0]
	s_add_i32 s25, s25, 2
	v_mfma_scale_f32_16x16x128_f8f6f4 v[56:59], v[12:19], v[216:223], v[56:59], v187, v185 op_sel_hi:[0,0,0]
	s_add_u32 s8, s8, 0x100
	s_addc_u32 s9, s9, 0
	v_mfma_scale_f32_16x16x128_f8f6f4 v[52:55], v[4:11], v[216:223], v[52:55], v187, v185 op_sel_hi:[0,0,0]
	s_add_u32 s19, s19, 0x100
	s_addc_u32 s24, s24, 0
	v_mfma_scale_f32_16x16x128_f8f6f4 v[40:43], v[12:19], v[224:231], v[40:43], v187, v185 op_sel_hi:[0,0,0]
	s_cmp_gt_u32 s25, 13
	v_mfma_scale_f32_16x16x128_f8f6f4 v[36:39], v[4:11], v[224:231], v[36:39], v187, v185 op_sel_hi:[0,0,0]
	s_setprio 0
	s_barrier
	s_cbranch_scc0 .LBB0_1891
	v_readlane_b32 s8, v255, 13
	v_readlane_b32 s9, v255, 14
	s_and_b64 vcc, exec, s[8:9]
	s_cbranch_vccz .LBB0_1894
	s_barrier

.LBB0_2329:
	s_add_i32 s43, s12, 2
	v_add_u32_e32 v156, s83, v142
	v_add_u32_e32 v172, s44, v142
	s_add_u32 s10, s8, 0x100
	ds_read_b128 v[144:147], v156
	ds_read_b128 v[148:151], v156 offset:1024
	ds_read_b128 v[152:155], v156 offset:2048
	ds_read_b128 v[156:159], v156 offset:3072
	ds_read_b128 v[160:163], v172
	ds_read_b128 v[164:167], v172 offset:1024
	ds_read_b128 v[168:171], v172 offset:2048
	ds_read_b128 v[172:175], v172 offset:3072
	s_addc_u32 s11, s9, 0
	s_cmp_lg_u32 s42, s12
	s_cselect_b32 s46, s10, 0
	s_cselect_b32 s47, s11, 0
	s_add_u32 s12, s6, s46
	s_addc_u32 s13, s7, s47
	s_add_u32 s46, s4, s46
	s_addc_u32 s47, s5, s47
	v_lshl_add_u64 v[208:209], v[138:139], 0, s[8:9]
	s_add_i32 m0, s22, 0xc000
	ds_read_b128 v[176:179], v143
	ds_read_b128 v[180:183], v143 offset:1024
	ds_read_b128 v[184:187], v143 offset:2048
	ds_read_b128 v[188:191], v143 offset:3072
	ds_read_b128 v[192:195], v143 offset:4096
	ds_read_b128 v[196:199], v143 offset:5120
	ds_read_b128 v[200:203], v143 offset:6144
	ds_read_b128 v[204:207], v143 offset:7168
	global_load_lds_dwordx4 v[208:209], off
	v_lshl_add_u64 v[208:209], v[140:141], 0, s[8:9]
	s_add_i32 m0, s22, 0xe000
	s_nop 0
	global_load_lds_dwordx4 v[208:209], off
	s_waitcnt vmcnt(8)
	s_waitcnt lgkmcnt(0)
	s_setprio 1
	s_barrier
	v_mfma_f32_16x16x32_bf16 v[124:127], v[144:147], v[176:179], v[124:127]
	v_mfma_f32_16x16x32_bf16 v[124:127], v[148:151], v[180:183], v[124:127]
	v_mfma_f32_16x16x32_bf16 v[112:115], v[144:147], v[184:187], v[112:115]
	v_mfma_f32_16x16x32_bf16 v[112:115], v[148:151], v[188:191], v[112:115]
	v_mfma_f32_16x16x32_bf16 v[96:99], v[144:147], v[192:195], v[96:99]
	v_mfma_f32_16x16x32_bf16 v[96:99], v[148:151], v[196:199], v[96:99]
	v_mfma_f32_16x16x32_bf16 v[80:83], v[144:147], v[200:203], v[80:83]
	v_mfma_f32_16x16x32_bf16 v[80:83], v[148:151], v[204:207], v[80:83]
	v_mfma_f32_16x16x32_bf16 v[76:79], v[152:155], v[200:203], v[76:79]
	v_mfma_f32_16x16x32_bf16 v[76:79], v[156:159], v[204:207], v[76:79]
	v_mfma_f32_16x16x32_bf16 v[92:95], v[152:155], v[192:195], v[92:95]
	v_mfma_f32_16x16x32_bf16 v[92:95], v[156:159], v[196:199], v[92:95]
	v_mfma_f32_16x16x32_bf16 v[108:111], v[152:155], v[184:187], v[108:111]
	v_mfma_f32_16x16x32_bf16 v[108:111], v[156:159], v[188:191], v[108:111]
	v_mfma_f32_16x16x32_bf16 v[128:131], v[152:155], v[176:179], v[128:131]
	v_mfma_f32_16x16x32_bf16 v[128:131], v[156:159], v[180:183], v[128:131]
	s_setprio 0
	s_setprio 1
	v_mfma_f32_16x16x32_bf16 v[120:123], v[160:163], v[176:179], v[120:123]
	v_mfma_f32_16x16x32_bf16 v[120:123], v[164:167], v[180:183], v[120:123]
	v_mfma_f32_16x16x32_bf16 v[104:107], v[160:163], v[184:187], v[104:107]
	v_mfma_f32_16x16x32_bf16 v[104:107], v[164:167], v[188:191], v[104:107]
	v_mfma_f32_16x16x32_bf16 v[88:91], v[160:163], v[192:195], v[88:91]
	v_mfma_f32_16x16x32_bf16 v[88:91], v[164:167], v[196:199], v[88:91]
	v_mfma_f32_16x16x32_bf16 v[72:75], v[160:163], v[200:203], v[72:75]
	v_mfma_f32_16x16x32_bf16 v[72:75], v[164:167], v[204:207], v[72:75]
	v_mfma_f32_16x16x32_bf16 v[68:71], v[168:171], v[200:203], v[68:71]
	v_mfma_f32_16x16x32_bf16 v[68:71], v[172:175], v[204:207], v[68:71]
	v_mfma_f32_16x16x32_bf16 v[84:87], v[168:171], v[192:195], v[84:87]
	v_mfma_f32_16x16x32_bf16 v[84:87], v[172:175], v[196:199], v[84:87]
	v_mfma_f32_16x16x32_bf16 v[100:103], v[168:171], v[184:187], v[100:103]
	v_mfma_f32_16x16x32_bf16 v[100:103], v[172:175], v[188:191], v[100:103]
	v_mfma_f32_16x16x32_bf16 v[116:119], v[168:171], v[176:179], v[116:119]
	v_mfma_f32_16x16x32_bf16 v[116:119], v[172:175], v[180:183], v[116:119]
	s_setprio 0
	s_barrier
	s_mov_b32 m0, s18
	v_lshl_add_u64 v[208:209], s[46:47], 0, v[2:3]
	s_add_u32 s8, s46, s2
	ds_read_b128 v[176:179], v143 offset:16384
	ds_read_b128 v[180:183], v143 offset:17408
	ds_read_b128 v[184:187], v143 offset:18432
	ds_read_b128 v[188:191], v143 offset:19456
	ds_read_b128 v[192:195], v143 offset:20480
	ds_read_b128 v[196:199], v143 offset:21504
	ds_read_b128 v[200:203], v143 offset:22528
	ds_read_b128 v[204:207], v143 offset:23552
	global_load_lds_dwordx4 v[208:209], off
	v_lshl_add_u64 v[210:211], s[46:47], 0, v[136:137]
	s_mov_b32 m0, s19
	s_addc_u32 s9, s47, s3
	global_load_lds_dwordx4 v[210:211], off
	v_lshl_add_u64 v[216:217], s[8:9], 0, v[2:3]
	s_mov_b32 m0, s20
	v_lshl_add_u64 v[218:219], s[8:9], 0, v[136:137]
	global_load_lds_dwordx4 v[216:217], off
	s_mov_b32 m0, s21
	v_lshl_add_u64 v[220:221], s[12:13], 0, v[132:133]
	global_load_lds_dwordx4 v[218:219], off
	s_mov_b32 m0, s22
	v_lshl_add_u64 v[222:223], s[12:13], 0, v[134:135]
	global_load_lds_dwordx4 v[220:221], off
	s_mov_b32 m0, s23
	s_nop 0
	global_load_lds_dwordx4 v[222:223], off
	s_waitcnt vmcnt(8)
	s_waitcnt lgkmcnt(0)
	s_setprio 1
	s_barrier
	v_mfma_f32_16x16x32_bf16 v[64:67], v[144:147], v[176:179], v[64:67]
	v_mfma_f32_16x16x32_bf16 v[64:67], v[148:151], v[180:183], v[64:67]
	v_mfma_f32_16x16x32_bf16 v[48:51], v[144:147], v[184:187], v[48:51]
	v_mfma_f32_16x16x32_bf16 v[48:51], v[148:151], v[188:191], v[48:51]
	v_mfma_f32_16x16x32_bf16 v[32:35], v[144:147], v[192:195], v[32:35]
	v_mfma_f32_16x16x32_bf16 v[32:35], v[148:151], v[196:199], v[32:35]
	v_mfma_f32_16x16x32_bf16 v[16:19], v[144:147], v[200:203], v[16:19]
	v_mfma_f32_16x16x32_bf16 v[16:19], v[148:151], v[204:207], v[16:19]
	v_mfma_f32_16x16x32_bf16 v[12:15], v[152:155], v[200:203], v[12:15]
	v_mfma_f32_16x16x32_bf16 v[12:15], v[156:159], v[204:207], v[12:15]
	v_mfma_f32_16x16x32_bf16 v[28:31], v[152:155], v[192:195], v[28:31]
	v_mfma_f32_16x16x32_bf16 v[28:31], v[156:159], v[196:199], v[28:31]
	v_mfma_f32_16x16x32_bf16 v[44:47], v[152:155], v[184:187], v[44:47]
	v_mfma_f32_16x16x32_bf16 v[44:47], v[156:159], v[188:191], v[44:47]
	v_mfma_f32_16x16x32_bf16 v[60:63], v[152:155], v[176:179], v[60:63]
	v_mfma_f32_16x16x32_bf16 v[60:63], v[156:159], v[180:183], v[60:63]
	s_setprio 0
	s_setprio 1
	v_mfma_f32_16x16x32_bf16 v[56:59], v[160:163], v[176:179], v[56:59]
	v_mfma_f32_16x16x32_bf16 v[56:59], v[164:167], v[180:183], v[56:59]
	v_mfma_f32_16x16x32_bf16 v[40:43], v[160:163], v[184:187], v[40:43]
	v_mfma_f32_16x16x32_bf16 v[40:43], v[164:167], v[188:191], v[40:43]
	v_mfma_f32_16x16x32_bf16 v[24:27], v[160:163], v[192:195], v[24:27]
	v_mfma_f32_16x16x32_bf16 v[24:27], v[164:167], v[196:199], v[24:27]
	v_mfma_f32_16x16x32_bf16 v[8:11], v[160:163], v[200:203], v[8:11]
	v_mfma_f32_16x16x32_bf16 v[8:11], v[164:167], v[204:207], v[8:11]
	v_mfma_f32_16x16x32_bf16 v[4:7], v[168:171], v[200:203], v[4:7]
	v_mfma_f32_16x16x32_bf16 v[4:7], v[172:175], v[204:207], v[4:7]
	v_mfma_f32_16x16x32_bf16 v[20:23], v[168:171], v[192:195], v[20:23]
	v_mfma_f32_16x16x32_bf16 v[20:23], v[172:175], v[196:199], v[20:23]
	v_mfma_f32_16x16x32_bf16 v[36:39], v[168:171], v[184:187], v[36:39]
	v_mfma_f32_16x16x32_bf16 v[36:39], v[172:175], v[188:191], v[36:39]
	v_mfma_f32_16x16x32_bf16 v[52:55], v[168:171], v[176:179], v[52:55]
	v_mfma_f32_16x16x32_bf16 v[52:55], v[172:175], v[180:183], v[52:55]
	s_setprio 0
	s_barrier
	v_add_u32_e32 v156, s45, v142
	v_add_u32_e32 v172, s74, v142
	ds_read_b128 v[144:147], v156
	ds_read_b128 v[148:151], v156 offset:1024
	ds_read_b128 v[152:155], v156 offset:2048
	ds_read_b128 v[156:159], v156 offset:3072
	ds_read_b128 v[160:163], v172
	ds_read_b128 v[164:167], v172 offset:1024
	ds_read_b128 v[168:171], v172 offset:2048
	ds_read_b128 v[172:175], v172 offset:3072
	s_add_u32 s8, s12, s2
	s_addc_u32 s9, s13, s3
	s_mov_b32 m0, s24
	v_lshl_add_u64 v[224:225], s[8:9], 0, v[132:133]
	ds_read_b128 v[176:179], v143 offset:32768
	ds_read_b128 v[180:183], v143 offset:33792
	ds_read_b128 v[184:187], v143 offset:34816
	ds_read_b128 v[188:191], v143 offset:35840
	ds_read_b128 v[192:195], v143 offset:36864
	ds_read_b128 v[196:199], v143 offset:37888
	ds_read_b128 v[200:203], v143 offset:38912
	ds_read_b128 v[204:207], v143 offset:39936
	global_load_lds_dwordx4 v[224:225], off
	v_lshl_add_u64 v[224:225], s[8:9], 0, v[134:135]
	s_mov_b32 m0, s25
	s_nop 0
	global_load_lds_dwordx4 v[224:225], off
	s_waitcnt vmcnt(8)
	s_waitcnt lgkmcnt(0)
	s_setprio 1
	s_barrier
	v_mfma_f32_16x16x32_bf16 v[124:127], v[144:147], v[176:179], v[124:127]
	v_mfma_f32_16x16x32_bf16 v[124:127], v[148:151], v[180:183], v[124:127]
	v_mfma_f32_16x16x32_bf16 v[112:115], v[144:147], v[184:187], v[112:115]
	v_mfma_f32_16x16x32_bf16 v[112:115], v[148:151], v[188:191], v[112:115]
	v_mfma_f32_16x16x32_bf16 v[96:99], v[144:147], v[192:195], v[96:99]
	v_mfma_f32_16x16x32_bf16 v[96:99], v[148:151], v[196:199], v[96:99]
	v_mfma_f32_16x16x32_bf16 v[80:83], v[144:147], v[200:203], v[80:83]
	v_mfma_f32_16x16x32_bf16 v[80:83], v[148:151], v[204:207], v[80:83]
	v_mfma_f32_16x16x32_bf16 v[76:79], v[152:155], v[200:203], v[76:79]
	v_mfma_f32_16x16x32_bf16 v[76:79], v[156:159], v[204:207], v[76:79]
	v_mfma_f32_16x16x32_bf16 v[92:95], v[152:155], v[192:195], v[92:95]
	v_mfma_f32_16x16x32_bf16 v[92:95], v[156:159], v[196:199], v[92:95]
	v_mfma_f32_16x16x32_bf16 v[108:111], v[152:155], v[184:187], v[108:111]
	v_mfma_f32_16x16x32_bf16 v[108:111], v[156:159], v[188:191], v[108:111]
	v_mfma_f32_16x16x32_bf16 v[128:131], v[152:155], v[176:179], v[128:131]
	v_mfma_f32_16x16x32_bf16 v[128:131], v[156:159], v[180:183], v[128:131]
	s_setprio 0
	s_setprio 1
	v_mfma_f32_16x16x32_bf16 v[120:123], v[160:163], v[176:179], v[120:123]
	v_mfma_f32_16x16x32_bf16 v[120:123], v[164:167], v[180:183], v[120:123]
	v_mfma_f32_16x16x32_bf16 v[104:107], v[160:163], v[184:187], v[104:107]
	v_mfma_f32_16x16x32_bf16 v[104:107], v[164:167], v[188:191], v[104:107]
	v_mfma_f32_16x16x32_bf16 v[88:91], v[160:163], v[192:195], v[88:91]
	v_mfma_f32_16x16x32_bf16 v[88:91], v[164:167], v[196:199], v[88:91]
	v_mfma_f32_16x16x32_bf16 v[72:75], v[160:163], v[200:203], v[72:75]
	v_mfma_f32_16x16x32_bf16 v[72:75], v[164:167], v[204:207], v[72:75]
	v_mfma_f32_16x16x32_bf16 v[68:71], v[168:171], v[200:203], v[68:71]
	v_mfma_f32_16x16x32_bf16 v[68:71], v[172:175], v[204:207], v[68:71]
	v_mfma_f32_16x16x32_bf16 v[84:87], v[168:171], v[192:195], v[84:87]
	v_mfma_f32_16x16x32_bf16 v[84:87], v[172:175], v[196:199], v[84:87]
	v_mfma_f32_16x16x32_bf16 v[100:103], v[168:171], v[184:187], v[100:103]
	v_mfma_f32_16x16x32_bf16 v[100:103], v[172:175], v[188:191], v[100:103]
	v_mfma_f32_16x16x32_bf16 v[116:119], v[168:171], v[176:179], v[116:119]
	v_mfma_f32_16x16x32_bf16 v[116:119], v[172:175], v[180:183], v[116:119]
	s_setprio 0
	s_barrier
	s_mov_b32 m0, s26
	v_lshl_add_u64 v[208:209], v[208:209], 0, s[64:65]
	ds_read_b128 v[176:179], v143 offset:49152
	ds_read_b128 v[180:183], v143 offset:50176
	ds_read_b128 v[184:187], v143 offset:51200
	ds_read_b128 v[188:191], v143 offset:52224
	ds_read_b128 v[192:195], v143 offset:53248
	ds_read_b128 v[196:199], v143 offset:54272
	ds_read_b128 v[200:203], v143 offset:55296
	ds_read_b128 v[204:207], v143 offset:56320
	global_load_lds_dwordx4 v[208:209], off
	v_lshl_add_u64 v[208:209], v[210:211], 0, s[64:65]
	s_mov_b32 m0, s27
	s_nop 0
	global_load_lds_dwordx4 v[208:209], off
	v_lshl_add_u64 v[208:209], v[216:217], 0, s[64:65]
	s_mov_b32 m0, s37
	s_nop 0
	global_load_lds_dwordx4 v[208:209], off
	v_lshl_add_u64 v[208:209], v[218:219], 0, s[64:65]
	s_mov_b32 m0, s40
	s_nop 0
	global_load_lds_dwordx4 v[208:209], off
	v_lshl_add_u64 v[208:209], v[220:221], 0, s[64:65]
	s_mov_b32 m0, s34
	s_nop 0
	global_load_lds_dwordx4 v[208:209], off
	v_lshl_add_u64 v[208:209], v[222:223], 0, s[64:65]
	s_mov_b32 m0, s35
	s_nop 0
	global_load_lds_dwordx4 v[208:209], off
	s_waitcnt vmcnt(8)
	s_waitcnt lgkmcnt(0)
	s_setprio 1
	s_barrier
	v_mfma_f32_16x16x32_bf16 v[64:67], v[144:147], v[176:179], v[64:67]
	v_mfma_f32_16x16x32_bf16 v[64:67], v[148:151], v[180:183], v[64:67]
	v_mfma_f32_16x16x32_bf16 v[48:51], v[144:147], v[184:187], v[48:51]
	v_mfma_f32_16x16x32_bf16 v[48:51], v[148:151], v[188:191], v[48:51]
	v_mfma_f32_16x16x32_bf16 v[32:35], v[144:147], v[192:195], v[32:35]
	v_mfma_f32_16x16x32_bf16 v[32:35], v[148:151], v[196:199], v[32:35]
	v_mfma_f32_16x16x32_bf16 v[16:19], v[144:147], v[200:203], v[16:19]
	v_mfma_f32_16x16x32_bf16 v[16:19], v[148:151], v[204:207], v[16:19]
	v_mfma_f32_16x16x32_bf16 v[12:15], v[152:155], v[200:203], v[12:15]
	v_mfma_f32_16x16x32_bf16 v[12:15], v[156:159], v[204:207], v[12:15]
	v_mfma_f32_16x16x32_bf16 v[28:31], v[152:155], v[192:195], v[28:31]
	v_mfma_f32_16x16x32_bf16 v[28:31], v[156:159], v[196:199], v[28:31]
	v_mfma_f32_16x16x32_bf16 v[44:47], v[152:155], v[184:187], v[44:47]
	v_mfma_f32_16x16x32_bf16 v[44:47], v[156:159], v[188:191], v[44:47]
	v_mfma_f32_16x16x32_bf16 v[60:63], v[152:155], v[176:179], v[60:63]
	v_mfma_f32_16x16x32_bf16 v[60:63], v[156:159], v[180:183], v[60:63]
	s_setprio 0
	s_setprio 1
	v_mfma_f32_16x16x32_bf16 v[56:59], v[160:163], v[176:179], v[56:59]
	v_mfma_f32_16x16x32_bf16 v[56:59], v[164:167], v[180:183], v[56:59]
	v_mfma_f32_16x16x32_bf16 v[40:43], v[160:163], v[184:187], v[40:43]
	v_mfma_f32_16x16x32_bf16 v[40:43], v[164:167], v[188:191], v[40:43]
	v_mfma_f32_16x16x32_bf16 v[24:27], v[160:163], v[192:195], v[24:27]
	v_mfma_f32_16x16x32_bf16 v[24:27], v[164:167], v[196:199], v[24:27]
	v_mfma_f32_16x16x32_bf16 v[8:11], v[160:163], v[200:203], v[8:11]
	v_mfma_f32_16x16x32_bf16 v[8:11], v[164:167], v[204:207], v[8:11]
	v_mfma_f32_16x16x32_bf16 v[4:7], v[168:171], v[200:203], v[4:7]
	v_mfma_f32_16x16x32_bf16 v[4:7], v[172:175], v[204:207], v[4:7]
	v_mfma_f32_16x16x32_bf16 v[20:23], v[168:171], v[192:195], v[20:23]
	v_mfma_f32_16x16x32_bf16 v[20:23], v[172:175], v[196:199], v[20:23]
	v_mfma_f32_16x16x32_bf16 v[36:39], v[168:171], v[184:187], v[36:39]
	v_mfma_f32_16x16x32_bf16 v[36:39], v[172:175], v[188:191], v[36:39]
	v_mfma_f32_16x16x32_bf16 v[52:55], v[168:171], v[176:179], v[52:55]
	v_mfma_f32_16x16x32_bf16 v[52:55], v[172:175], v[180:183], v[52:55]
	s_setprio 0
	s_barrier
	s_cmp_ge_i32 s43, s41
	s_mov_b64 s[8:9], s[10:11]
	s_mov_b32 s12, s43
	s_cbranch_scc0 .LBB0_2329

.LBB0_2890:
	v_add_u32_e32 v4, s18, v184
	v_add_u32_e32 v8, s19, v184
	s_add_u32 s14, s48, s12
	ds_read_b128 v[28:31], v4
	ds_read_b128 v[32:35], v4 offset:16
	ds_read_b128 v[20:23], v4 offset:2048
	ds_read_b128 v[24:27], v4 offset:2064
	ds_read_b128 v[12:15], v8
	ds_read_b128 v[16:19], v8 offset:16
	ds_read_b128 v[4:7], v8 offset:2048
	ds_read_b128 v[8:11], v8 offset:2064
	s_addc_u32 s15, s49, s13
	s_add_u32 s14, s14, 0x45c00100
	s_addc_u32 s15, s15, 0
	s_add_u32 s53, s50, s12
	s_addc_u32 s56, s51, s13
	s_cmpk_eq_i32 s12, 0x700
	s_cselect_b32 s25, s11, s15
	s_cselect_b32 s24, s10, s14
	s_cselect_b32 s15, s3, s56
	s_cselect_b32 s14, s2, s53
	v_lshl_add_u64 v[210:211], v[170:171], 0, s[12:13]
	s_add_i32 m0, s37, 0xc000
	ds_read_b128 v[174:177], v185
	ds_read_b128 v[178:181], v185 offset:16
	ds_read_b128 v[186:189], v185 offset:2048
	ds_read_b128 v[190:193], v185 offset:2064
	ds_read_b128 v[194:197], v185 offset:4096
	ds_read_b128 v[198:201], v185 offset:4112
	ds_read_b128 v[202:205], v185 offset:6144
	ds_read_b128 v[206:209], v185 offset:6160
	global_load_lds_dwordx4 v[210:211], off
	v_lshl_add_u64 v[210:211], v[172:173], 0, s[12:13]
	s_add_i32 m0, s37, 0xe000
	s_nop 0
	global_load_lds_dwordx4 v[210:211], off
	s_waitcnt vmcnt(8)
	s_waitcnt lgkmcnt(0)
	s_setprio 1
	s_barrier
	v_mfma_scale_f32_16x16x128_f8f6f4 v[160:163], v[28:35], v[174:181], v[160:163], v183, v182 op_sel_hi:[0,0,0]
	v_mfma_scale_f32_16x16x128_f8f6f4 v[156:159], v[20:27], v[174:181], v[156:159], v183, v182 op_sel_hi:[0,0,0]
	v_mfma_scale_f32_16x16x128_f8f6f4 v[144:147], v[28:35], v[186:193], v[144:147], v183, v182 op_sel_hi:[0,0,0]
	v_mfma_scale_f32_16x16x128_f8f6f4 v[140:143], v[20:27], v[186:193], v[140:143], v183, v182 op_sel_hi:[0,0,0]
	v_mfma_scale_f32_16x16x128_f8f6f4 v[128:131], v[28:35], v[194:201], v[128:131], v183, v182 op_sel_hi:[0,0,0]
	v_mfma_scale_f32_16x16x128_f8f6f4 v[124:127], v[20:27], v[194:201], v[124:127], v183, v182 op_sel_hi:[0,0,0]
	v_mfma_scale_f32_16x16x128_f8f6f4 v[112:115], v[28:35], v[202:209], v[112:115], v183, v182 op_sel_hi:[0,0,0]
	v_mfma_scale_f32_16x16x128_f8f6f4 v[108:111], v[20:27], v[202:209], v[108:111], v183, v182 op_sel_hi:[0,0,0]
	s_setprio 0
	s_setprio 1
	v_mfma_scale_f32_16x16x128_f8f6f4 v[152:155], v[12:19], v[174:181], v[152:155], v183, v182 op_sel_hi:[0,0,0]
	v_mfma_scale_f32_16x16x128_f8f6f4 v[148:151], v[4:11], v[174:181], v[148:151], v183, v182 op_sel_hi:[0,0,0]
	v_mfma_scale_f32_16x16x128_f8f6f4 v[136:139], v[12:19], v[186:193], v[136:139], v183, v182 op_sel_hi:[0,0,0]
	v_mfma_scale_f32_16x16x128_f8f6f4 v[132:135], v[4:11], v[186:193], v[132:135], v183, v182 op_sel_hi:[0,0,0]
	v_mfma_scale_f32_16x16x128_f8f6f4 v[120:123], v[12:19], v[194:201], v[120:123], v183, v182 op_sel_hi:[0,0,0]
	v_mfma_scale_f32_16x16x128_f8f6f4 v[116:119], v[4:11], v[194:201], v[116:119], v183, v182 op_sel_hi:[0,0,0]
	v_mfma_scale_f32_16x16x128_f8f6f4 v[104:107], v[12:19], v[202:209], v[104:107], v183, v182 op_sel_hi:[0,0,0]
	v_mfma_scale_f32_16x16x128_f8f6f4 v[100:103], v[4:11], v[202:209], v[100:103], v183, v182 op_sel_hi:[0,0,0]
	s_setprio 0
	s_barrier
	s_mov_b32 m0, s23
	v_lshl_add_u64 v[174:175], s[14:15], 0, v[2:3]
	s_add_u32 s56, s14, 0x40000
	ds_read_b128 v[186:189], v185 offset:16384
	ds_read_b128 v[190:193], v185 offset:16400
	ds_read_b128 v[194:197], v185 offset:18432
	ds_read_b128 v[198:201], v185 offset:18448
	ds_read_b128 v[202:205], v185 offset:20480
	ds_read_b128 v[206:209], v185 offset:20496
	ds_read_b128 v[216:219], v185 offset:22528
	ds_read_b128 v[220:223], v185 offset:22544
	global_load_lds_dwordx4 v[174:175], off
	v_lshl_add_u64 v[176:177], s[14:15], 0, v[168:169]
	s_mov_b32 m0, s26
	s_addc_u32 s57, s15, 0
	global_load_lds_dwordx4 v[176:177], off
	v_lshl_add_u64 v[178:179], s[56:57], 0, v[2:3]
	s_mov_b32 m0, s27
	v_lshl_add_u64 v[180:181], s[24:25], 0, v[166:167]
	global_load_lds_dwordx4 v[178:179], off
	v_lshl_add_u64 v[178:179], s[56:57], 0, v[168:169]
	s_mov_b32 m0, s34
	s_nop 0
	global_load_lds_dwordx4 v[178:179], off
	v_lshl_add_u64 v[178:179], s[24:25], 0, v[164:165]
	s_mov_b32 m0, s37
	s_nop 0
	global_load_lds_dwordx4 v[178:179], off
	s_mov_b32 m0, s38
	s_nop 0
	global_load_lds_dwordx4 v[180:181], off
	s_waitcnt vmcnt(8)
	s_waitcnt lgkmcnt(0)
	s_setprio 1
	s_barrier
	v_mfma_scale_f32_16x16x128_f8f6f4 v[96:99], v[28:35], v[186:193], v[96:99], v183, v182 op_sel_hi:[0,0,0]
	v_mfma_scale_f32_16x16x128_f8f6f4 v[92:95], v[20:27], v[186:193], v[92:95], v183, v182 op_sel_hi:[0,0,0]
	v_mfma_scale_f32_16x16x128_f8f6f4 v[80:83], v[28:35], v[194:201], v[80:83], v183, v182 op_sel_hi:[0,0,0]
	v_mfma_scale_f32_16x16x128_f8f6f4 v[76:79], v[20:27], v[194:201], v[76:79], v183, v182 op_sel_hi:[0,0,0]
	v_mfma_scale_f32_16x16x128_f8f6f4 v[64:67], v[28:35], v[202:209], v[64:67], v183, v182 op_sel_hi:[0,0,0]
	v_mfma_scale_f32_16x16x128_f8f6f4 v[60:63], v[20:27], v[202:209], v[60:63], v183, v182 op_sel_hi:[0,0,0]
	v_mfma_scale_f32_16x16x128_f8f6f4 v[48:51], v[28:35], v[216:223], v[48:51], v183, v182 op_sel_hi:[0,0,0]
	v_mfma_scale_f32_16x16x128_f8f6f4 v[44:47], v[20:27], v[216:223], v[44:47], v183, v182 op_sel_hi:[0,0,0]
	s_setprio 0
	s_setprio 1
	v_mfma_scale_f32_16x16x128_f8f6f4 v[88:91], v[12:19], v[186:193], v[88:91], v183, v182 op_sel_hi:[0,0,0]
	v_mfma_scale_f32_16x16x128_f8f6f4 v[84:87], v[4:11], v[186:193], v[84:87], v183, v182 op_sel_hi:[0,0,0]
	v_mfma_scale_f32_16x16x128_f8f6f4 v[72:75], v[12:19], v[194:201], v[72:75], v183, v182 op_sel_hi:[0,0,0]
	v_mfma_scale_f32_16x16x128_f8f6f4 v[68:71], v[4:11], v[194:201], v[68:71], v183, v182 op_sel_hi:[0,0,0]
	v_mfma_scale_f32_16x16x128_f8f6f4 v[56:59], v[12:19], v[202:209], v[56:59], v183, v182 op_sel_hi:[0,0,0]
	v_mfma_scale_f32_16x16x128_f8f6f4 v[52:55], v[4:11], v[202:209], v[52:55], v183, v182 op_sel_hi:[0,0,0]
	v_mfma_scale_f32_16x16x128_f8f6f4 v[40:43], v[12:19], v[216:223], v[40:43], v183, v182 op_sel_hi:[0,0,0]
	v_mfma_scale_f32_16x16x128_f8f6f4 v[36:39], v[4:11], v[216:223], v[36:39], v183, v182 op_sel_hi:[0,0,0]
	s_setprio 0
	s_barrier
	v_add_u32_e32 v4, s20, v184
	v_add_u32_e32 v8, s21, v184
	ds_read_b128 v[28:31], v4
	ds_read_b128 v[32:35], v4 offset:16
	ds_read_b128 v[20:23], v4 offset:2048
	ds_read_b128 v[24:27], v4 offset:2064
	ds_read_b128 v[12:15], v8
	ds_read_b128 v[16:19], v8 offset:16
	ds_read_b128 v[4:7], v8 offset:2048
	ds_read_b128 v[8:11], v8 offset:2064
	s_add_u32 s24, s24, 0x40000
	s_addc_u32 s25, s25, 0
	s_mov_b32 m0, s39
	v_lshl_add_u64 v[210:211], s[24:25], 0, v[164:165]
	ds_read_b128 v[186:189], v185 offset:32768
	ds_read_b128 v[190:193], v185 offset:32784
	ds_read_b128 v[194:197], v185 offset:34816
	ds_read_b128 v[198:201], v185 offset:34832
	ds_read_b128 v[202:205], v185 offset:36864
	ds_read_b128 v[206:209], v185 offset:36880
	ds_read_b128 v[216:219], v185 offset:38912
	ds_read_b128 v[220:223], v185 offset:38928
	global_load_lds_dwordx4 v[210:211], off
	v_lshl_add_u64 v[210:211], s[24:25], 0, v[166:167]
	s_mov_b32 m0, s40
	s_nop 0
	global_load_lds_dwordx4 v[210:211], off
	s_waitcnt vmcnt(8)
	s_waitcnt lgkmcnt(0)
	s_setprio 1
	s_barrier
	v_mfma_scale_f32_16x16x128_f8f6f4 v[160:163], v[28:35], v[186:193], v[160:163], v183, v182 op_sel_hi:[0,0,0]
	v_mfma_scale_f32_16x16x128_f8f6f4 v[156:159], v[20:27], v[186:193], v[156:159], v183, v182 op_sel_hi:[0,0,0]
	v_mfma_scale_f32_16x16x128_f8f6f4 v[144:147], v[28:35], v[194:201], v[144:147], v183, v182 op_sel_hi:[0,0,0]
	v_mfma_scale_f32_16x16x128_f8f6f4 v[140:143], v[20:27], v[194:201], v[140:143], v183, v182 op_sel_hi:[0,0,0]
	v_mfma_scale_f32_16x16x128_f8f6f4 v[128:131], v[28:35], v[202:209], v[128:131], v183, v182 op_sel_hi:[0,0,0]
	v_mfma_scale_f32_16x16x128_f8f6f4 v[124:127], v[20:27], v[202:209], v[124:127], v183, v182 op_sel_hi:[0,0,0]
	v_mfma_scale_f32_16x16x128_f8f6f4 v[112:115], v[28:35], v[216:223], v[112:115], v183, v182 op_sel_hi:[0,0,0]
	v_mfma_scale_f32_16x16x128_f8f6f4 v[108:111], v[20:27], v[216:223], v[108:111], v183, v182 op_sel_hi:[0,0,0]
	s_setprio 0
	s_setprio 1
	v_mfma_scale_f32_16x16x128_f8f6f4 v[152:155], v[12:19], v[186:193], v[152:155], v183, v182 op_sel_hi:[0,0,0]
	v_mfma_scale_f32_16x16x128_f8f6f4 v[148:151], v[4:11], v[186:193], v[148:151], v183, v182 op_sel_hi:[0,0,0]
	v_mfma_scale_f32_16x16x128_f8f6f4 v[136:139], v[12:19], v[194:201], v[136:139], v183, v182 op_sel_hi:[0,0,0]
	v_mfma_scale_f32_16x16x128_f8f6f4 v[132:135], v[4:11], v[194:201], v[132:135], v183, v182 op_sel_hi:[0,0,0]
	v_mfma_scale_f32_16x16x128_f8f6f4 v[120:123], v[12:19], v[202:209], v[120:123], v183, v182 op_sel_hi:[0,0,0]
	v_mfma_scale_f32_16x16x128_f8f6f4 v[116:119], v[4:11], v[202:209], v[116:119], v183, v182 op_sel_hi:[0,0,0]
	v_mfma_scale_f32_16x16x128_f8f6f4 v[104:107], v[12:19], v[216:223], v[104:107], v183, v182 op_sel_hi:[0,0,0]
	v_mfma_scale_f32_16x16x128_f8f6f4 v[100:103], v[4:11], v[216:223], v[100:103], v183, v182 op_sel_hi:[0,0,0]
	s_setprio 0
	s_barrier
	s_mov_b32 m0, s42
	v_lshl_add_u64 v[174:175], v[174:175], 0, s[64:65]
	s_add_u32 s14, s14, 0x40080
	ds_read_b128 v[186:189], v185 offset:49152
	ds_read_b128 v[190:193], v185 offset:49168
	ds_read_b128 v[194:197], v185 offset:51200
	ds_read_b128 v[198:201], v185 offset:51216
	ds_read_b128 v[202:205], v185 offset:53248
	ds_read_b128 v[206:209], v185 offset:53264
	ds_read_b128 v[216:219], v185 offset:55296
	ds_read_b128 v[220:223], v185 offset:55312
	global_load_lds_dwordx4 v[174:175], off
	v_lshl_add_u64 v[174:175], v[176:177], 0, s[64:65]
	s_mov_b32 m0, s43
	s_addc_u32 s15, s15, 0
	global_load_lds_dwordx4 v[174:175], off
	v_lshl_add_u64 v[174:175], s[14:15], 0, v[2:3]
	s_mov_b32 m0, s46
	s_nop 0
	global_load_lds_dwordx4 v[174:175], off
	v_lshl_add_u64 v[174:175], s[14:15], 0, v[168:169]
	s_mov_b32 m0, s47
	s_nop 0
	global_load_lds_dwordx4 v[174:175], off
	v_lshl_add_u64 v[174:175], v[178:179], 0, s[64:65]
	s_mov_b32 m0, s44
	s_nop 0
	global_load_lds_dwordx4 v[174:175], off
	v_lshl_add_u64 v[174:175], v[180:181], 0, s[64:65]
	s_mov_b32 m0, s45
	s_nop 0
	global_load_lds_dwordx4 v[174:175], off
	s_waitcnt vmcnt(8)
	s_waitcnt lgkmcnt(0)
	s_setprio 1
	s_barrier
	v_mfma_scale_f32_16x16x128_f8f6f4 v[96:99], v[28:35], v[186:193], v[96:99], v183, v182 op_sel_hi:[0,0,0]
	v_mfma_scale_f32_16x16x128_f8f6f4 v[92:95], v[20:27], v[186:193], v[92:95], v183, v182 op_sel_hi:[0,0,0]
	v_mfma_scale_f32_16x16x128_f8f6f4 v[80:83], v[28:35], v[194:201], v[80:83], v183, v182 op_sel_hi:[0,0,0]
	v_mfma_scale_f32_16x16x128_f8f6f4 v[76:79], v[20:27], v[194:201], v[76:79], v183, v182 op_sel_hi:[0,0,0]
	v_mfma_scale_f32_16x16x128_f8f6f4 v[64:67], v[28:35], v[202:209], v[64:67], v183, v182 op_sel_hi:[0,0,0]
	v_mfma_scale_f32_16x16x128_f8f6f4 v[60:63], v[20:27], v[202:209], v[60:63], v183, v182 op_sel_hi:[0,0,0]
	v_mfma_scale_f32_16x16x128_f8f6f4 v[48:51], v[28:35], v[216:223], v[48:51], v183, v182 op_sel_hi:[0,0,0]
	v_mfma_scale_f32_16x16x128_f8f6f4 v[44:47], v[20:27], v[216:223], v[44:47], v183, v182 op_sel_hi:[0,0,0]
	s_setprio 0
	s_setprio 1
	v_mfma_scale_f32_16x16x128_f8f6f4 v[88:91], v[12:19], v[186:193], v[88:91], v183, v182 op_sel_hi:[0,0,0]
	v_mfma_scale_f32_16x16x128_f8f6f4 v[84:87], v[4:11], v[186:193], v[84:87], v183, v182 op_sel_hi:[0,0,0]
	v_mfma_scale_f32_16x16x128_f8f6f4 v[72:75], v[12:19], v[194:201], v[72:75], v183, v182 op_sel_hi:[0,0,0]
	v_mfma_scale_f32_16x16x128_f8f6f4 v[68:71], v[4:11], v[194:201], v[68:71], v183, v182 op_sel_hi:[0,0,0]
	s_add_i32 s52, s52, 2
	v_mfma_scale_f32_16x16x128_f8f6f4 v[56:59], v[12:19], v[202:209], v[56:59], v183, v182 op_sel_hi:[0,0,0]
	s_add_u32 s12, s12, 0x100
	s_addc_u32 s13, s13, 0
	v_mfma_scale_f32_16x16x128_f8f6f4 v[52:55], v[4:11], v[202:209], v[52:55], v183, v182 op_sel_hi:[0,0,0]
	s_cmp_gt_u32 s52, 13
	v_mfma_scale_f32_16x16x128_f8f6f4 v[40:43], v[12:19], v[216:223], v[40:43], v183, v182 op_sel_hi:[0,0,0]
	v_mfma_scale_f32_16x16x128_f8f6f4 v[36:39], v[4:11], v[216:223], v[36:39], v183, v182 op_sel_hi:[0,0,0]
	s_setprio 0
	s_barrier
	s_cbranch_scc0 .LBB0_2890
	s_cmpk_lt_u32 s22, 0x100
	s_cbranch_scc0 .LBB0_2893
	s_barrier

.LBB0_2896:
	v_add_u32_e32 v148, s18, v126
	v_add_u32_e32 v172, s19, v126
	s_add_u32 s12, s46, s8
	ds_read_b128 v[128:131], v148
	ds_read_b128 v[132:135], v148 offset:1024
	ds_read_b128 v[140:143], v148 offset:2048
	ds_read_b128 v[148:151], v148 offset:3072
	ds_read_b128 v[160:163], v172
	ds_read_b128 v[164:167], v172 offset:1024
	ds_read_b128 v[168:171], v172 offset:2048
	ds_read_b128 v[172:175], v172 offset:3072
	s_addc_u32 s13, s47, s9
	s_add_u32 s12, s12, 0x34400100
	s_addc_u32 s13, s13, 0
	s_add_u32 s16, s48, s8
	s_addc_u32 s51, s49, s9
	s_cmpk_eq_i32 s8, 0xf00
	s_cselect_b32 s15, s11, s13
	s_cselect_b32 s14, s10, s12
	s_cselect_b32 s13, s3, s51
	s_cselect_b32 s12, s2, s16
	v_lshl_add_u64 v[208:209], v[122:123], 0, s[8:9]
	s_add_i32 m0, s27, 0xc000
	ds_read_b128 v[176:179], v127
	ds_read_b128 v[180:183], v127 offset:1024
	ds_read_b128 v[184:187], v127 offset:2048
	ds_read_b128 v[188:191], v127 offset:3072
	ds_read_b128 v[192:195], v127 offset:4096
	ds_read_b128 v[196:199], v127 offset:5120
	ds_read_b128 v[200:203], v127 offset:6144
	ds_read_b128 v[204:207], v127 offset:7168
	global_load_lds_dwordx4 v[208:209], off
	v_lshl_add_u64 v[208:209], v[124:125], 0, s[8:9]
	s_add_i32 m0, s27, 0xe000
	s_nop 0
	global_load_lds_dwordx4 v[208:209], off
	s_waitcnt vmcnt(8)
	s_waitcnt lgkmcnt(0)
	s_setprio 1
	s_barrier
	v_mfma_f32_16x16x32_bf16 v[156:159], v[128:131], v[176:179], v[156:159]
	v_mfma_f32_16x16x32_bf16 v[156:159], v[132:135], v[180:183], v[156:159]
	v_mfma_f32_16x16x32_bf16 v[112:115], v[128:131], v[184:187], v[112:115]
	v_mfma_f32_16x16x32_bf16 v[112:115], v[132:135], v[188:191], v[112:115]
	v_mfma_f32_16x16x32_bf16 v[96:99], v[128:131], v[192:195], v[96:99]
	v_mfma_f32_16x16x32_bf16 v[96:99], v[132:135], v[196:199], v[96:99]
	v_mfma_f32_16x16x32_bf16 v[80:83], v[128:131], v[200:203], v[80:83]
	v_mfma_f32_16x16x32_bf16 v[80:83], v[132:135], v[204:207], v[80:83]
	v_mfma_f32_16x16x32_bf16 v[76:79], v[140:143], v[200:203], v[76:79]
	v_mfma_f32_16x16x32_bf16 v[76:79], v[148:151], v[204:207], v[76:79]
	v_mfma_f32_16x16x32_bf16 v[92:95], v[140:143], v[192:195], v[92:95]
	v_mfma_f32_16x16x32_bf16 v[92:95], v[148:151], v[196:199], v[92:95]
	v_mfma_f32_16x16x32_bf16 v[108:111], v[140:143], v[184:187], v[108:111]
	v_mfma_f32_16x16x32_bf16 v[108:111], v[148:151], v[188:191], v[108:111]
	v_mfma_f32_16x16x32_bf16 v[152:155], v[140:143], v[176:179], v[152:155]
	v_mfma_f32_16x16x32_bf16 v[152:155], v[148:151], v[180:183], v[152:155]
	s_setprio 0
	s_setprio 1
	v_mfma_f32_16x16x32_bf16 v[144:147], v[160:163], v[176:179], v[144:147]
	v_mfma_f32_16x16x32_bf16 v[144:147], v[164:167], v[180:183], v[144:147]
	v_mfma_f32_16x16x32_bf16 v[104:107], v[160:163], v[184:187], v[104:107]
	v_mfma_f32_16x16x32_bf16 v[104:107], v[164:167], v[188:191], v[104:107]
	v_mfma_f32_16x16x32_bf16 v[88:91], v[160:163], v[192:195], v[88:91]
	v_mfma_f32_16x16x32_bf16 v[88:91], v[164:167], v[196:199], v[88:91]
	v_mfma_f32_16x16x32_bf16 v[72:75], v[160:163], v[200:203], v[72:75]
	v_mfma_f32_16x16x32_bf16 v[72:75], v[164:167], v[204:207], v[72:75]
	v_mfma_f32_16x16x32_bf16 v[68:71], v[168:171], v[200:203], v[68:71]
	v_mfma_f32_16x16x32_bf16 v[68:71], v[172:175], v[204:207], v[68:71]
	v_mfma_f32_16x16x32_bf16 v[84:87], v[168:171], v[192:195], v[84:87]
	v_mfma_f32_16x16x32_bf16 v[84:87], v[172:175], v[196:199], v[84:87]
	v_mfma_f32_16x16x32_bf16 v[100:103], v[168:171], v[184:187], v[100:103]
	v_mfma_f32_16x16x32_bf16 v[100:103], v[172:175], v[188:191], v[100:103]
	v_mfma_f32_16x16x32_bf16 v[136:139], v[168:171], v[176:179], v[136:139]
	v_mfma_f32_16x16x32_bf16 v[136:139], v[172:175], v[180:183], v[136:139]
	s_setprio 0
	s_barrier
	s_mov_b32 m0, s23
	v_lshl_add_u64 v[208:209], s[12:13], 0, v[2:3]
	s_add_u32 s52, s12, 0x80000
	ds_read_b128 v[176:179], v127 offset:16384
	ds_read_b128 v[180:183], v127 offset:17408
	ds_read_b128 v[184:187], v127 offset:18432
	ds_read_b128 v[188:191], v127 offset:19456
	ds_read_b128 v[192:195], v127 offset:20480
	ds_read_b128 v[196:199], v127 offset:21504
	ds_read_b128 v[200:203], v127 offset:22528
	ds_read_b128 v[204:207], v127 offset:23552
	global_load_lds_dwordx4 v[208:209], off
	v_lshl_add_u64 v[210:211], s[12:13], 0, v[120:121]
	s_mov_b32 m0, s24
	s_addc_u32 s53, s13, 0
	global_load_lds_dwordx4 v[210:211], off
	v_lshl_add_u64 v[216:217], s[52:53], 0, v[2:3]
	s_mov_b32 m0, s25
	v_lshl_add_u64 v[218:219], s[14:15], 0, v[118:119]
	global_load_lds_dwordx4 v[216:217], off
	v_lshl_add_u64 v[216:217], s[52:53], 0, v[120:121]
	s_mov_b32 m0, s26
	s_nop 0
	global_load_lds_dwordx4 v[216:217], off
	v_lshl_add_u64 v[216:217], s[14:15], 0, v[116:117]
	s_mov_b32 m0, s27
	s_nop 0
	global_load_lds_dwordx4 v[216:217], off
	s_mov_b32 m0, s35
	s_nop 0
	global_load_lds_dwordx4 v[218:219], off
	s_waitcnt vmcnt(8)
	s_waitcnt lgkmcnt(0)
	s_setprio 1
	s_barrier
	v_mfma_f32_16x16x32_bf16 v[64:67], v[128:131], v[176:179], v[64:67]
	v_mfma_f32_16x16x32_bf16 v[64:67], v[132:135], v[180:183], v[64:67]
	v_mfma_f32_16x16x32_bf16 v[48:51], v[128:131], v[184:187], v[48:51]
	v_mfma_f32_16x16x32_bf16 v[48:51], v[132:135], v[188:191], v[48:51]
	v_mfma_f32_16x16x32_bf16 v[32:35], v[128:131], v[192:195], v[32:35]
	v_mfma_f32_16x16x32_bf16 v[32:35], v[132:135], v[196:199], v[32:35]
	v_mfma_f32_16x16x32_bf16 v[16:19], v[128:131], v[200:203], v[16:19]
	v_mfma_f32_16x16x32_bf16 v[16:19], v[132:135], v[204:207], v[16:19]
	v_mfma_f32_16x16x32_bf16 v[12:15], v[140:143], v[200:203], v[12:15]
	v_mfma_f32_16x16x32_bf16 v[12:15], v[148:151], v[204:207], v[12:15]
	v_mfma_f32_16x16x32_bf16 v[28:31], v[140:143], v[192:195], v[28:31]
	v_mfma_f32_16x16x32_bf16 v[28:31], v[148:151], v[196:199], v[28:31]
	v_mfma_f32_16x16x32_bf16 v[44:47], v[140:143], v[184:187], v[44:47]
	v_mfma_f32_16x16x32_bf16 v[44:47], v[148:151], v[188:191], v[44:47]
	v_mfma_f32_16x16x32_bf16 v[60:63], v[140:143], v[176:179], v[60:63]
	v_mfma_f32_16x16x32_bf16 v[60:63], v[148:151], v[180:183], v[60:63]
	s_setprio 0
	s_setprio 1
	v_mfma_f32_16x16x32_bf16 v[56:59], v[160:163], v[176:179], v[56:59]
	v_mfma_f32_16x16x32_bf16 v[56:59], v[164:167], v[180:183], v[56:59]
	v_mfma_f32_16x16x32_bf16 v[40:43], v[160:163], v[184:187], v[40:43]
	v_mfma_f32_16x16x32_bf16 v[40:43], v[164:167], v[188:191], v[40:43]
	v_mfma_f32_16x16x32_bf16 v[24:27], v[160:163], v[192:195], v[24:27]
	v_mfma_f32_16x16x32_bf16 v[24:27], v[164:167], v[196:199], v[24:27]
	v_mfma_f32_16x16x32_bf16 v[8:11], v[160:163], v[200:203], v[8:11]
	v_mfma_f32_16x16x32_bf16 v[8:11], v[164:167], v[204:207], v[8:11]
	v_mfma_f32_16x16x32_bf16 v[4:7], v[168:171], v[200:203], v[4:7]
	v_mfma_f32_16x16x32_bf16 v[4:7], v[172:175], v[204:207], v[4:7]
	v_mfma_f32_16x16x32_bf16 v[20:23], v[168:171], v[192:195], v[20:23]
	v_mfma_f32_16x16x32_bf16 v[20:23], v[172:175], v[196:199], v[20:23]
	v_mfma_f32_16x16x32_bf16 v[36:39], v[168:171], v[184:187], v[36:39]
	v_mfma_f32_16x16x32_bf16 v[36:39], v[172:175], v[188:191], v[36:39]
	v_mfma_f32_16x16x32_bf16 v[52:55], v[168:171], v[176:179], v[52:55]
	v_mfma_f32_16x16x32_bf16 v[52:55], v[172:175], v[180:183], v[52:55]
	s_setprio 0
	s_barrier
	v_add_u32_e32 v148, s20, v126
	v_add_u32_e32 v172, s21, v126
	ds_read_b128 v[128:131], v148
	ds_read_b128 v[132:135], v148 offset:1024
	ds_read_b128 v[140:143], v148 offset:2048
	ds_read_b128 v[148:151], v148 offset:3072
	ds_read_b128 v[160:163], v172
	ds_read_b128 v[164:167], v172 offset:1024
	ds_read_b128 v[168:171], v172 offset:2048
	ds_read_b128 v[172:175], v172 offset:3072
	s_add_u32 s14, s14, 0x80000
	s_addc_u32 s15, s15, 0
	s_mov_b32 m0, s37
	v_lshl_add_u64 v[220:221], s[14:15], 0, v[116:117]
	ds_read_b128 v[176:179], v127 offset:32768
	ds_read_b128 v[180:183], v127 offset:33792
	ds_read_b128 v[184:187], v127 offset:34816
	ds_read_b128 v[188:191], v127 offset:35840
	ds_read_b128 v[192:195], v127 offset:36864
	ds_read_b128 v[196:199], v127 offset:37888
	ds_read_b128 v[200:203], v127 offset:38912
	ds_read_b128 v[204:207], v127 offset:39936
	global_load_lds_dwordx4 v[220:221], off
	v_lshl_add_u64 v[220:221], s[14:15], 0, v[118:119]
	s_mov_b32 m0, s38
	s_nop 0
	global_load_lds_dwordx4 v[220:221], off
	s_waitcnt vmcnt(8)
	s_waitcnt lgkmcnt(0)
	s_setprio 1
	s_barrier
	v_mfma_f32_16x16x32_bf16 v[156:159], v[128:131], v[176:179], v[156:159]
	v_mfma_f32_16x16x32_bf16 v[156:159], v[132:135], v[180:183], v[156:159]
	v_mfma_f32_16x16x32_bf16 v[112:115], v[128:131], v[184:187], v[112:115]
	v_mfma_f32_16x16x32_bf16 v[112:115], v[132:135], v[188:191], v[112:115]
	v_mfma_f32_16x16x32_bf16 v[96:99], v[128:131], v[192:195], v[96:99]
	v_mfma_f32_16x16x32_bf16 v[96:99], v[132:135], v[196:199], v[96:99]
	v_mfma_f32_16x16x32_bf16 v[80:83], v[128:131], v[200:203], v[80:83]
	v_mfma_f32_16x16x32_bf16 v[80:83], v[132:135], v[204:207], v[80:83]
	v_mfma_f32_16x16x32_bf16 v[76:79], v[140:143], v[200:203], v[76:79]
	v_mfma_f32_16x16x32_bf16 v[76:79], v[148:151], v[204:207], v[76:79]
	v_mfma_f32_16x16x32_bf16 v[92:95], v[140:143], v[192:195], v[92:95]
	v_mfma_f32_16x16x32_bf16 v[92:95], v[148:151], v[196:199], v[92:95]
	v_mfma_f32_16x16x32_bf16 v[108:111], v[140:143], v[184:187], v[108:111]
	v_mfma_f32_16x16x32_bf16 v[108:111], v[148:151], v[188:191], v[108:111]
	v_mfma_f32_16x16x32_bf16 v[152:155], v[140:143], v[176:179], v[152:155]
	v_mfma_f32_16x16x32_bf16 v[152:155], v[148:151], v[180:183], v[152:155]
	s_setprio 0
	s_setprio 1
	v_mfma_f32_16x16x32_bf16 v[144:147], v[160:163], v[176:179], v[144:147]
	v_mfma_f32_16x16x32_bf16 v[144:147], v[164:167], v[180:183], v[144:147]
	v_mfma_f32_16x16x32_bf16 v[104:107], v[160:163], v[184:187], v[104:107]
	v_mfma_f32_16x16x32_bf16 v[104:107], v[164:167], v[188:191], v[104:107]
	v_mfma_f32_16x16x32_bf16 v[88:91], v[160:163], v[192:195], v[88:91]
	v_mfma_f32_16x16x32_bf16 v[88:91], v[164:167], v[196:199], v[88:91]
	v_mfma_f32_16x16x32_bf16 v[72:75], v[160:163], v[200:203], v[72:75]
	v_mfma_f32_16x16x32_bf16 v[72:75], v[164:167], v[204:207], v[72:75]
	v_mfma_f32_16x16x32_bf16 v[68:71], v[168:171], v[200:203], v[68:71]
	v_mfma_f32_16x16x32_bf16 v[68:71], v[172:175], v[204:207], v[68:71]
	v_mfma_f32_16x16x32_bf16 v[84:87], v[168:171], v[192:195], v[84:87]
	v_mfma_f32_16x16x32_bf16 v[84:87], v[172:175], v[196:199], v[84:87]
	v_mfma_f32_16x16x32_bf16 v[100:103], v[168:171], v[184:187], v[100:103]
	v_mfma_f32_16x16x32_bf16 v[100:103], v[172:175], v[188:191], v[100:103]
	v_mfma_f32_16x16x32_bf16 v[136:139], v[168:171], v[176:179], v[136:139]
	v_mfma_f32_16x16x32_bf16 v[136:139], v[172:175], v[180:183], v[136:139]
	s_setprio 0
	s_barrier
	s_mov_b32 m0, s40
	v_lshl_add_u64 v[208:209], v[208:209], 0, s[64:65]
	s_add_u32 s12, s12, 0x80080
	ds_read_b128 v[176:179], v127 offset:49152
	ds_read_b128 v[180:183], v127 offset:50176
	ds_read_b128 v[184:187], v127 offset:51200
	ds_read_b128 v[188:191], v127 offset:52224
	ds_read_b128 v[192:195], v127 offset:53248
	ds_read_b128 v[196:199], v127 offset:54272
	ds_read_b128 v[200:203], v127 offset:55296
	ds_read_b128 v[204:207], v127 offset:56320
	global_load_lds_dwordx4 v[208:209], off
	v_lshl_add_u64 v[208:209], v[210:211], 0, s[64:65]
	s_mov_b32 m0, s41
	s_addc_u32 s13, s13, 0
	global_load_lds_dwordx4 v[208:209], off
	v_lshl_add_u64 v[208:209], s[12:13], 0, v[2:3]
	s_mov_b32 m0, s44
	s_nop 0
	global_load_lds_dwordx4 v[208:209], off
	v_lshl_add_u64 v[208:209], s[12:13], 0, v[120:121]
	s_mov_b32 m0, s45
	s_nop 0
	global_load_lds_dwordx4 v[208:209], off
	v_lshl_add_u64 v[208:209], v[216:217], 0, s[64:65]
	s_mov_b32 m0, s42
	s_nop 0
	global_load_lds_dwordx4 v[208:209], off
	v_lshl_add_u64 v[208:209], v[218:219], 0, s[64:65]
	s_mov_b32 m0, s43
	s_nop 0
	global_load_lds_dwordx4 v[208:209], off
	s_waitcnt vmcnt(8)
	s_waitcnt lgkmcnt(0)
	s_setprio 1
	s_barrier
	v_mfma_f32_16x16x32_bf16 v[64:67], v[128:131], v[176:179], v[64:67]
	v_mfma_f32_16x16x32_bf16 v[64:67], v[132:135], v[180:183], v[64:67]
	v_mfma_f32_16x16x32_bf16 v[48:51], v[128:131], v[184:187], v[48:51]
	v_mfma_f32_16x16x32_bf16 v[48:51], v[132:135], v[188:191], v[48:51]
	v_mfma_f32_16x16x32_bf16 v[32:35], v[128:131], v[192:195], v[32:35]
	v_mfma_f32_16x16x32_bf16 v[32:35], v[132:135], v[196:199], v[32:35]
	v_mfma_f32_16x16x32_bf16 v[16:19], v[128:131], v[200:203], v[16:19]
	v_mfma_f32_16x16x32_bf16 v[16:19], v[132:135], v[204:207], v[16:19]
	v_mfma_f32_16x16x32_bf16 v[12:15], v[140:143], v[200:203], v[12:15]
	v_mfma_f32_16x16x32_bf16 v[12:15], v[148:151], v[204:207], v[12:15]
	v_mfma_f32_16x16x32_bf16 v[28:31], v[140:143], v[192:195], v[28:31]
	v_mfma_f32_16x16x32_bf16 v[28:31], v[148:151], v[196:199], v[28:31]
	v_mfma_f32_16x16x32_bf16 v[44:47], v[140:143], v[184:187], v[44:47]
	v_mfma_f32_16x16x32_bf16 v[44:47], v[148:151], v[188:191], v[44:47]
	v_mfma_f32_16x16x32_bf16 v[60:63], v[140:143], v[176:179], v[60:63]
	v_mfma_f32_16x16x32_bf16 v[60:63], v[148:151], v[180:183], v[60:63]
	s_setprio 0
	s_setprio 1
	v_mfma_f32_16x16x32_bf16 v[56:59], v[160:163], v[176:179], v[56:59]
	v_mfma_f32_16x16x32_bf16 v[56:59], v[164:167], v[180:183], v[56:59]
	v_mfma_f32_16x16x32_bf16 v[40:43], v[160:163], v[184:187], v[40:43]
	v_mfma_f32_16x16x32_bf16 v[40:43], v[164:167], v[188:191], v[40:43]
	v_mfma_f32_16x16x32_bf16 v[24:27], v[160:163], v[192:195], v[24:27]
	v_mfma_f32_16x16x32_bf16 v[24:27], v[164:167], v[196:199], v[24:27]
	v_mfma_f32_16x16x32_bf16 v[8:11], v[160:163], v[200:203], v[8:11]
	v_mfma_f32_16x16x32_bf16 v[8:11], v[164:167], v[204:207], v[8:11]
	s_add_i32 s50, s50, 2
	v_mfma_f32_16x16x32_bf16 v[4:7], v[168:171], v[200:203], v[4:7]
	v_mfma_f32_16x16x32_bf16 v[4:7], v[172:175], v[204:207], v[4:7]
	s_add_u32 s8, s8, 0x100
	s_addc_u32 s9, s9, 0
	v_mfma_f32_16x16x32_bf16 v[20:23], v[168:171], v[192:195], v[20:23]
	v_mfma_f32_16x16x32_bf16 v[20:23], v[172:175], v[196:199], v[20:23]
	s_cmp_gt_u32 s50, 29
	v_mfma_f32_16x16x32_bf16 v[36:39], v[168:171], v[184:187], v[36:39]
	v_mfma_f32_16x16x32_bf16 v[36:39], v[172:175], v[188:191], v[36:39]
	v_mfma_f32_16x16x32_bf16 v[52:55], v[168:171], v[176:179], v[52:55]
	v_mfma_f32_16x16x32_bf16 v[52:55], v[172:175], v[180:183], v[52:55]
	s_setprio 0
	s_barrier
	s_cbranch_scc0 .LBB0_2896
	s_cmpk_lt_u32 s22, 0x100
	s_cbranch_scc0 .LBB0_2899
	s_barrier

.LBB0_3116:
	v_add_u32_e32 v142, s26, v144
	ds_read_b128 v[146:149], v142
	ds_read_b128 v[150:153], v142 offset:1024
	ds_read_b128 v[154:157], v142 offset:2048
	ds_read_b128 v[158:161], v142 offset:3072
	v_add_u32_e32 v142, s40, v144
	ds_read_b128 v[162:165], v142
	ds_read_b128 v[166:169], v142 offset:1024
	ds_read_b128 v[170:173], v142 offset:2048
	ds_read_b128 v[174:177], v142 offset:3072
	s_add_u32 s18, s34, 0xfff80080
	s_addc_u32 s19, s35, -1
	s_cmp_eq_u32 s74, 28
	s_cselect_b32 s39, s13, s19
	s_cselect_b32 s38, s69, s18
	s_cselect_b32 s19, s11, s73
	s_cselect_b32 s18, s70, s71
	v_lshl_add_u64 v[142:143], s[34:35], 0, v[138:139]
	s_add_i32 m0, s43, 0xc000
	ds_read_b128 v[178:181], v145
	ds_read_b128 v[182:185], v145 offset:1024
	ds_read_b128 v[186:189], v145 offset:2048
	ds_read_b128 v[190:193], v145 offset:3072
	ds_read_b128 v[194:197], v145 offset:4096
	ds_read_b128 v[198:201], v145 offset:5120
	ds_read_b128 v[202:205], v145 offset:6144
	ds_read_b128 v[206:209], v145 offset:7168
	global_load_lds_dwordx4 v[142:143], off
	v_lshl_add_u64 v[142:143], s[34:35], 0, v[140:141]
	s_add_i32 m0, s43, 0xe000
	s_nop 0
	global_load_lds_dwordx4 v[142:143], off
	s_waitcnt vmcnt(8)
	s_waitcnt lgkmcnt(0)
	s_setprio 1
	s_barrier
	v_mfma_f32_16x16x32_bf16 v[128:131], v[146:149], v[178:181], v[128:131]
	v_mfma_f32_16x16x32_bf16 v[128:131], v[150:153], v[182:185], v[128:131]
	v_mfma_f32_16x16x32_bf16 v[112:115], v[146:149], v[186:189], v[112:115]
	v_mfma_f32_16x16x32_bf16 v[112:115], v[150:153], v[190:193], v[112:115]
	v_mfma_f32_16x16x32_bf16 v[96:99], v[146:149], v[194:197], v[96:99]
	v_mfma_f32_16x16x32_bf16 v[96:99], v[150:153], v[198:201], v[96:99]
	v_mfma_f32_16x16x32_bf16 v[80:83], v[146:149], v[202:205], v[80:83]
	v_mfma_f32_16x16x32_bf16 v[80:83], v[150:153], v[206:209], v[80:83]
	v_mfma_f32_16x16x32_bf16 v[72:75], v[154:157], v[202:205], v[72:75]
	v_mfma_f32_16x16x32_bf16 v[72:75], v[158:161], v[206:209], v[72:75]
	v_mfma_f32_16x16x32_bf16 v[88:91], v[154:157], v[194:197], v[88:91]
	v_mfma_f32_16x16x32_bf16 v[88:91], v[158:161], v[198:201], v[88:91]
	v_mfma_f32_16x16x32_bf16 v[104:107], v[154:157], v[186:189], v[104:107]
	v_mfma_f32_16x16x32_bf16 v[104:107], v[158:161], v[190:193], v[104:107]
	v_mfma_f32_16x16x32_bf16 v[120:123], v[154:157], v[178:181], v[120:123]
	v_mfma_f32_16x16x32_bf16 v[120:123], v[158:161], v[182:185], v[120:123]
	s_setprio 0
	s_setprio 1
	v_mfma_f32_16x16x32_bf16 v[124:127], v[162:165], v[178:181], v[124:127]
	v_mfma_f32_16x16x32_bf16 v[124:127], v[166:169], v[182:185], v[124:127]
	v_mfma_f32_16x16x32_bf16 v[108:111], v[162:165], v[186:189], v[108:111]
	v_mfma_f32_16x16x32_bf16 v[108:111], v[166:169], v[190:193], v[108:111]
	v_mfma_f32_16x16x32_bf16 v[92:95], v[162:165], v[194:197], v[92:95]
	v_mfma_f32_16x16x32_bf16 v[92:95], v[166:169], v[198:201], v[92:95]
	v_mfma_f32_16x16x32_bf16 v[76:79], v[162:165], v[202:205], v[76:79]
	v_mfma_f32_16x16x32_bf16 v[76:79], v[166:169], v[206:209], v[76:79]
	v_mfma_f32_16x16x32_bf16 v[68:71], v[170:173], v[202:205], v[68:71]
	v_mfma_f32_16x16x32_bf16 v[68:71], v[174:177], v[206:209], v[68:71]
	v_mfma_f32_16x16x32_bf16 v[84:87], v[170:173], v[194:197], v[84:87]
	v_mfma_f32_16x16x32_bf16 v[84:87], v[174:177], v[198:201], v[84:87]
	v_mfma_f32_16x16x32_bf16 v[100:103], v[170:173], v[186:189], v[100:103]
	v_mfma_f32_16x16x32_bf16 v[100:103], v[174:177], v[190:193], v[100:103]
	v_mfma_f32_16x16x32_bf16 v[116:119], v[170:173], v[178:181], v[116:119]
	v_mfma_f32_16x16x32_bf16 v[116:119], v[174:177], v[182:185], v[116:119]
	s_setprio 0
	s_barrier
	s_mov_b32 m0, s27
	v_lshl_add_u64 v[142:143], s[18:19], 0, v[2:3]
	s_add_u32 s76, s18, 0x80000
	ds_read_b128 v[178:181], v145 offset:16384
	ds_read_b128 v[182:185], v145 offset:17408
	ds_read_b128 v[186:189], v145 offset:18432
	ds_read_b128 v[190:193], v145 offset:19456
	ds_read_b128 v[194:197], v145 offset:20480
	ds_read_b128 v[198:201], v145 offset:21504
	ds_read_b128 v[202:205], v145 offset:22528
	ds_read_b128 v[206:209], v145 offset:23552
	global_load_lds_dwordx4 v[142:143], off
	v_lshl_add_u64 v[210:211], s[18:19], 0, v[132:133]
	s_mov_b32 m0, s37
	s_addc_u32 s77, s19, 0
	global_load_lds_dwordx4 v[210:211], off
	v_lshl_add_u64 v[212:213], s[76:77], 0, v[2:3]
	s_mov_b32 m0, s41
	v_lshl_add_u64 v[214:215], s[38:39], 0, v[134:135]
	global_load_lds_dwordx4 v[212:213], off
	v_lshl_add_u64 v[212:213], s[76:77], 0, v[132:133]
	s_mov_b32 m0, s42
	s_nop 0
	global_load_lds_dwordx4 v[212:213], off
	v_lshl_add_u64 v[212:213], s[38:39], 0, v[136:137]
	s_mov_b32 m0, s43
	s_nop 0
	global_load_lds_dwordx4 v[212:213], off
	s_mov_b32 m0, s44
	s_nop 0
	global_load_lds_dwordx4 v[214:215], off
	s_waitcnt vmcnt(8)
	s_waitcnt lgkmcnt(0)
	s_setprio 1
	s_barrier
	v_mfma_f32_16x16x32_bf16 v[64:67], v[146:149], v[178:181], v[64:67]
	v_mfma_f32_16x16x32_bf16 v[64:67], v[150:153], v[182:185], v[64:67]
	v_mfma_f32_16x16x32_bf16 v[48:51], v[146:149], v[186:189], v[48:51]
	v_mfma_f32_16x16x32_bf16 v[48:51], v[150:153], v[190:193], v[48:51]
	v_mfma_f32_16x16x32_bf16 v[32:35], v[146:149], v[194:197], v[32:35]
	v_mfma_f32_16x16x32_bf16 v[32:35], v[150:153], v[198:201], v[32:35]
	v_mfma_f32_16x16x32_bf16 v[16:19], v[146:149], v[202:205], v[16:19]
	v_mfma_f32_16x16x32_bf16 v[16:19], v[150:153], v[206:209], v[16:19]
	v_mfma_f32_16x16x32_bf16 v[8:11], v[154:157], v[202:205], v[8:11]
	v_mfma_f32_16x16x32_bf16 v[8:11], v[158:161], v[206:209], v[8:11]
	v_mfma_f32_16x16x32_bf16 v[24:27], v[154:157], v[194:197], v[24:27]
	v_mfma_f32_16x16x32_bf16 v[24:27], v[158:161], v[198:201], v[24:27]
	v_mfma_f32_16x16x32_bf16 v[40:43], v[154:157], v[186:189], v[40:43]
	v_mfma_f32_16x16x32_bf16 v[40:43], v[158:161], v[190:193], v[40:43]
	v_mfma_f32_16x16x32_bf16 v[56:59], v[154:157], v[178:181], v[56:59]
	v_mfma_f32_16x16x32_bf16 v[56:59], v[158:161], v[182:185], v[56:59]
	s_setprio 0
	s_setprio 1
	v_mfma_f32_16x16x32_bf16 v[60:63], v[162:165], v[178:181], v[60:63]
	v_mfma_f32_16x16x32_bf16 v[60:63], v[166:169], v[182:185], v[60:63]
	v_mfma_f32_16x16x32_bf16 v[44:47], v[162:165], v[186:189], v[44:47]
	v_mfma_f32_16x16x32_bf16 v[44:47], v[166:169], v[190:193], v[44:47]
	v_mfma_f32_16x16x32_bf16 v[28:31], v[162:165], v[194:197], v[28:31]
	v_mfma_f32_16x16x32_bf16 v[28:31], v[166:169], v[198:201], v[28:31]
	v_mfma_f32_16x16x32_bf16 v[12:15], v[162:165], v[202:205], v[12:15]
	v_mfma_f32_16x16x32_bf16 v[12:15], v[166:169], v[206:209], v[12:15]
	v_mfma_f32_16x16x32_bf16 v[4:7], v[170:173], v[202:205], v[4:7]
	v_mfma_f32_16x16x32_bf16 v[4:7], v[174:177], v[206:209], v[4:7]
	v_mfma_f32_16x16x32_bf16 v[20:23], v[170:173], v[194:197], v[20:23]
	v_mfma_f32_16x16x32_bf16 v[20:23], v[174:177], v[198:201], v[20:23]
	v_mfma_f32_16x16x32_bf16 v[36:39], v[170:173], v[186:189], v[36:39]
	v_mfma_f32_16x16x32_bf16 v[36:39], v[174:177], v[190:193], v[36:39]
	v_mfma_f32_16x16x32_bf16 v[52:55], v[170:173], v[178:181], v[52:55]
	v_mfma_f32_16x16x32_bf16 v[52:55], v[174:177], v[182:185], v[52:55]
	s_setprio 0
	s_barrier
	v_add_u32_e32 v158, s49, v144
	v_add_u32_e32 v174, s56, v144
	ds_read_b128 v[146:149], v158
	ds_read_b128 v[150:153], v158 offset:1024
	ds_read_b128 v[154:157], v158 offset:2048
	ds_read_b128 v[158:161], v158 offset:3072
	ds_read_b128 v[162:165], v174
	ds_read_b128 v[166:169], v174 offset:1024
	ds_read_b128 v[170:173], v174 offset:2048
	ds_read_b128 v[174:177], v174 offset:3072
	s_add_u32 s38, s38, 0x80000
	s_addc_u32 s39, s39, 0
	s_mov_b32 m0, s45
	v_lshl_add_u64 v[216:217], s[38:39], 0, v[136:137]
	ds_read_b128 v[178:181], v145 offset:32768
	ds_read_b128 v[182:185], v145 offset:33792
	ds_read_b128 v[186:189], v145 offset:34816
	ds_read_b128 v[190:193], v145 offset:35840
	ds_read_b128 v[194:197], v145 offset:36864
	ds_read_b128 v[198:201], v145 offset:37888
	ds_read_b128 v[202:205], v145 offset:38912
	ds_read_b128 v[206:209], v145 offset:39936
	global_load_lds_dwordx4 v[216:217], off
	v_lshl_add_u64 v[216:217], s[38:39], 0, v[134:135]
	s_mov_b32 m0, s46
	s_nop 0
	global_load_lds_dwordx4 v[216:217], off
	s_waitcnt vmcnt(8)
	s_waitcnt lgkmcnt(0)
	s_setprio 1
	s_barrier
	v_mfma_f32_16x16x32_bf16 v[128:131], v[146:149], v[178:181], v[128:131]
	v_mfma_f32_16x16x32_bf16 v[128:131], v[150:153], v[182:185], v[128:131]
	v_mfma_f32_16x16x32_bf16 v[112:115], v[146:149], v[186:189], v[112:115]
	v_mfma_f32_16x16x32_bf16 v[112:115], v[150:153], v[190:193], v[112:115]
	v_mfma_f32_16x16x32_bf16 v[96:99], v[146:149], v[194:197], v[96:99]
	v_mfma_f32_16x16x32_bf16 v[96:99], v[150:153], v[198:201], v[96:99]
	v_mfma_f32_16x16x32_bf16 v[80:83], v[146:149], v[202:205], v[80:83]
	v_mfma_f32_16x16x32_bf16 v[80:83], v[150:153], v[206:209], v[80:83]
	v_mfma_f32_16x16x32_bf16 v[72:75], v[154:157], v[202:205], v[72:75]
	v_mfma_f32_16x16x32_bf16 v[72:75], v[158:161], v[206:209], v[72:75]
	v_mfma_f32_16x16x32_bf16 v[88:91], v[154:157], v[194:197], v[88:91]
	v_mfma_f32_16x16x32_bf16 v[88:91], v[158:161], v[198:201], v[88:91]
	v_mfma_f32_16x16x32_bf16 v[104:107], v[154:157], v[186:189], v[104:107]
	v_mfma_f32_16x16x32_bf16 v[104:107], v[158:161], v[190:193], v[104:107]
	v_mfma_f32_16x16x32_bf16 v[120:123], v[154:157], v[178:181], v[120:123]
	v_mfma_f32_16x16x32_bf16 v[120:123], v[158:161], v[182:185], v[120:123]
	s_setprio 0
	s_setprio 1
	v_mfma_f32_16x16x32_bf16 v[124:127], v[162:165], v[178:181], v[124:127]
	v_mfma_f32_16x16x32_bf16 v[124:127], v[166:169], v[182:185], v[124:127]
	v_mfma_f32_16x16x32_bf16 v[108:111], v[162:165], v[186:189], v[108:111]
	v_mfma_f32_16x16x32_bf16 v[108:111], v[166:169], v[190:193], v[108:111]
	v_mfma_f32_16x16x32_bf16 v[92:95], v[162:165], v[194:197], v[92:95]
	v_mfma_f32_16x16x32_bf16 v[92:95], v[166:169], v[198:201], v[92:95]
	v_mfma_f32_16x16x32_bf16 v[76:79], v[162:165], v[202:205], v[76:79]
	v_mfma_f32_16x16x32_bf16 v[76:79], v[166:169], v[206:209], v[76:79]
	v_mfma_f32_16x16x32_bf16 v[68:71], v[170:173], v[202:205], v[68:71]
	v_mfma_f32_16x16x32_bf16 v[68:71], v[174:177], v[206:209], v[68:71]
	v_mfma_f32_16x16x32_bf16 v[84:87], v[170:173], v[194:197], v[84:87]
	v_mfma_f32_16x16x32_bf16 v[84:87], v[174:177], v[198:201], v[84:87]
	v_mfma_f32_16x16x32_bf16 v[100:103], v[170:173], v[186:189], v[100:103]
	v_mfma_f32_16x16x32_bf16 v[100:103], v[174:177], v[190:193], v[100:103]
	v_mfma_f32_16x16x32_bf16 v[116:119], v[170:173], v[178:181], v[116:119]
	v_mfma_f32_16x16x32_bf16 v[116:119], v[174:177], v[182:185], v[116:119]
	s_setprio 0
	s_barrier
	s_mov_b32 m0, s50
	v_lshl_add_u64 v[142:143], v[142:143], 0, s[64:65]
	s_add_u32 s18, s18, 0x80080
	ds_read_b128 v[178:181], v145 offset:49152
	ds_read_b128 v[182:185], v145 offset:50176
	ds_read_b128 v[186:189], v145 offset:51200
	ds_read_b128 v[190:193], v145 offset:52224
	ds_read_b128 v[194:197], v145 offset:53248
	ds_read_b128 v[198:201], v145 offset:54272
	ds_read_b128 v[202:205], v145 offset:55296
	ds_read_b128 v[206:209], v145 offset:56320
	global_load_lds_dwordx4 v[142:143], off
	v_lshl_add_u64 v[142:143], v[210:211], 0, s[64:65]
	s_mov_b32 m0, s51
	s_addc_u32 s19, s19, 0
	global_load_lds_dwordx4 v[142:143], off
	v_lshl_add_u64 v[142:143], s[18:19], 0, v[2:3]
	s_mov_b32 m0, s57
	s_nop 0
	global_load_lds_dwordx4 v[142:143], off
	v_lshl_add_u64 v[142:143], s[18:19], 0, v[132:133]
	s_mov_b32 m0, s58
	s_nop 0
	global_load_lds_dwordx4 v[142:143], off
	v_lshl_add_u64 v[142:143], v[212:213], 0, s[64:65]
	s_mov_b32 m0, s52
	s_nop 0
	global_load_lds_dwordx4 v[142:143], off
	v_lshl_add_u64 v[142:143], v[214:215], 0, s[64:65]
	s_mov_b32 m0, s53
	s_nop 0
	global_load_lds_dwordx4 v[142:143], off
	s_waitcnt vmcnt(8)
	s_waitcnt lgkmcnt(0)
	s_setprio 1
	s_barrier
	v_mfma_f32_16x16x32_bf16 v[64:67], v[146:149], v[178:181], v[64:67]
	v_mfma_f32_16x16x32_bf16 v[64:67], v[150:153], v[182:185], v[64:67]
	v_mfma_f32_16x16x32_bf16 v[48:51], v[146:149], v[186:189], v[48:51]
	v_mfma_f32_16x16x32_bf16 v[48:51], v[150:153], v[190:193], v[48:51]
	v_mfma_f32_16x16x32_bf16 v[32:35], v[146:149], v[194:197], v[32:35]
	v_mfma_f32_16x16x32_bf16 v[32:35], v[150:153], v[198:201], v[32:35]
	v_mfma_f32_16x16x32_bf16 v[16:19], v[146:149], v[202:205], v[16:19]
	v_mfma_f32_16x16x32_bf16 v[16:19], v[150:153], v[206:209], v[16:19]
	v_mfma_f32_16x16x32_bf16 v[8:11], v[154:157], v[202:205], v[8:11]
	v_mfma_f32_16x16x32_bf16 v[8:11], v[158:161], v[206:209], v[8:11]
	v_mfma_f32_16x16x32_bf16 v[24:27], v[154:157], v[194:197], v[24:27]
	v_mfma_f32_16x16x32_bf16 v[24:27], v[158:161], v[198:201], v[24:27]
	v_mfma_f32_16x16x32_bf16 v[40:43], v[154:157], v[186:189], v[40:43]
	v_mfma_f32_16x16x32_bf16 v[40:43], v[158:161], v[190:193], v[40:43]
	v_mfma_f32_16x16x32_bf16 v[56:59], v[154:157], v[178:181], v[56:59]
	v_mfma_f32_16x16x32_bf16 v[56:59], v[158:161], v[182:185], v[56:59]
	s_setprio 0
	s_setprio 1
	v_mfma_f32_16x16x32_bf16 v[60:63], v[162:165], v[178:181], v[60:63]
	v_mfma_f32_16x16x32_bf16 v[60:63], v[166:169], v[182:185], v[60:63]
	v_mfma_f32_16x16x32_bf16 v[44:47], v[162:165], v[186:189], v[44:47]
	v_mfma_f32_16x16x32_bf16 v[44:47], v[166:169], v[190:193], v[44:47]
	v_mfma_f32_16x16x32_bf16 v[28:31], v[162:165], v[194:197], v[28:31]
	v_mfma_f32_16x16x32_bf16 v[28:31], v[166:169], v[198:201], v[28:31]
	v_mfma_f32_16x16x32_bf16 v[12:15], v[162:165], v[202:205], v[12:15]
	v_mfma_f32_16x16x32_bf16 v[12:15], v[166:169], v[206:209], v[12:15]
	s_add_i32 s74, s74, 2
	v_mfma_f32_16x16x32_bf16 v[4:7], v[170:173], v[202:205], v[4:7]
	v_mfma_f32_16x16x32_bf16 v[4:7], v[174:177], v[206:209], v[4:7]
	s_add_u32 s34, s34, 0x100
	s_addc_u32 s35, s35, 0
	v_mfma_f32_16x16x32_bf16 v[20:23], v[170:173], v[194:197], v[20:23]
	v_mfma_f32_16x16x32_bf16 v[20:23], v[174:177], v[198:201], v[20:23]
	s_add_u32 s71, s71, 0x100
	s_addc_u32 s73, s73, 0
	v_mfma_f32_16x16x32_bf16 v[36:39], v[170:173], v[186:189], v[36:39]
	v_mfma_f32_16x16x32_bf16 v[36:39], v[174:177], v[190:193], v[36:39]
	s_cmp_gt_u32 s74, 29
	v_mfma_f32_16x16x32_bf16 v[52:55], v[170:173], v[178:181], v[52:55]
	v_mfma_f32_16x16x32_bf16 v[52:55], v[174:177], v[182:185], v[52:55]
	s_setprio 0
	s_barrier
	s_cbranch_scc0 .LBB0_3116
	s_and_b64 vcc, exec, s[8:9]
	s_cbranch_vccz .LBB0_3119
	s_barrier

.LBB0_3195:
	v_add_u32_e32 v144, s26, v249
	v_add_u32_e32 v160, s38, v249
	ds_read_b128 v[132:135], v144
	ds_read_b128 v[136:139], v144 offset:1024
	ds_read_b128 v[140:143], v144 offset:2048
	ds_read_b128 v[144:147], v144 offset:3072
	ds_read_b128 v[148:151], v160
	ds_read_b128 v[152:155], v160 offset:1024
	ds_read_b128 v[156:159], v160 offset:2048
	ds_read_b128 v[160:163], v160 offset:3072
	s_add_u32 s24, s14, 0x100
	s_addc_u32 s25, s15, 0
	s_cmpk_eq_i32 s74, 0x54
	s_cselect_b32 s35, s5, s25
	s_cselect_b32 s34, s4, s24
	s_cselect_b32 s19, s13, s73
	s_cselect_b32 s18, s12, s71
	v_lshl_add_u64 v[196:197], s[14:15], 0, v[222:223]
	s_add_i32 m0, s41, 0xc000
	ds_read_b128 v[164:167], v250
	ds_read_b128 v[168:171], v250 offset:1024
	ds_read_b128 v[172:175], v250 offset:2048
	ds_read_b128 v[176:179], v250 offset:3072
	ds_read_b128 v[180:183], v250 offset:4096
	ds_read_b128 v[184:187], v250 offset:5120
	ds_read_b128 v[188:191], v250 offset:6144
	ds_read_b128 v[192:195], v250 offset:7168
	global_load_lds_dwordx4 v[196:197], off
	v_lshl_add_u64 v[196:197], s[14:15], 0, v[224:225]
	s_add_i32 m0, s41, 0xe000
	s_nop 0
	global_load_lds_dwordx4 v[196:197], off
	s_waitcnt vmcnt(8)
	s_waitcnt lgkmcnt(0)
	s_setprio 1
	s_barrier
	v_mfma_f32_16x16x32_bf16 v[128:131], v[132:135], v[164:167], v[128:131]
	v_mfma_f32_16x16x32_bf16 v[128:131], v[136:139], v[168:171], v[128:131]
	v_mfma_f32_16x16x32_bf16 v[112:115], v[132:135], v[172:175], v[112:115]
	v_mfma_f32_16x16x32_bf16 v[112:115], v[136:139], v[176:179], v[112:115]
	v_mfma_f32_16x16x32_bf16 v[96:99], v[132:135], v[180:183], v[96:99]
	v_mfma_f32_16x16x32_bf16 v[96:99], v[136:139], v[184:187], v[96:99]
	v_mfma_f32_16x16x32_bf16 v[80:83], v[132:135], v[188:191], v[80:83]
	v_mfma_f32_16x16x32_bf16 v[80:83], v[136:139], v[192:195], v[80:83]
	v_mfma_f32_16x16x32_bf16 v[76:79], v[140:143], v[188:191], v[76:79]
	v_mfma_f32_16x16x32_bf16 v[76:79], v[144:147], v[192:195], v[76:79]
	v_mfma_f32_16x16x32_bf16 v[92:95], v[140:143], v[180:183], v[92:95]
	v_mfma_f32_16x16x32_bf16 v[92:95], v[144:147], v[184:187], v[92:95]
	v_mfma_f32_16x16x32_bf16 v[108:111], v[140:143], v[172:175], v[108:111]
	v_mfma_f32_16x16x32_bf16 v[108:111], v[144:147], v[176:179], v[108:111]
	v_mfma_f32_16x16x32_bf16 v[124:127], v[140:143], v[164:167], v[124:127]
	v_mfma_f32_16x16x32_bf16 v[124:127], v[144:147], v[168:171], v[124:127]
	s_setprio 0
	s_setprio 1
	v_mfma_f32_16x16x32_bf16 v[120:123], v[148:151], v[164:167], v[120:123]
	v_mfma_f32_16x16x32_bf16 v[120:123], v[152:155], v[168:171], v[120:123]
	v_mfma_f32_16x16x32_bf16 v[104:107], v[148:151], v[172:175], v[104:107]
	v_mfma_f32_16x16x32_bf16 v[104:107], v[152:155], v[176:179], v[104:107]
	v_mfma_f32_16x16x32_bf16 v[88:91], v[148:151], v[180:183], v[88:91]
	v_mfma_f32_16x16x32_bf16 v[88:91], v[152:155], v[184:187], v[88:91]
	v_mfma_f32_16x16x32_bf16 v[72:75], v[148:151], v[188:191], v[72:75]
	v_mfma_f32_16x16x32_bf16 v[72:75], v[152:155], v[192:195], v[72:75]
	v_mfma_f32_16x16x32_bf16 v[68:71], v[156:159], v[188:191], v[68:71]
	v_mfma_f32_16x16x32_bf16 v[68:71], v[160:163], v[192:195], v[68:71]
	v_mfma_f32_16x16x32_bf16 v[84:87], v[156:159], v[180:183], v[84:87]
	v_mfma_f32_16x16x32_bf16 v[84:87], v[160:163], v[184:187], v[84:87]
	v_mfma_f32_16x16x32_bf16 v[100:103], v[156:159], v[172:175], v[100:103]
	v_mfma_f32_16x16x32_bf16 v[100:103], v[160:163], v[176:179], v[100:103]
	v_mfma_f32_16x16x32_bf16 v[116:119], v[156:159], v[164:167], v[116:119]
	v_mfma_f32_16x16x32_bf16 v[116:119], v[160:163], v[168:171], v[116:119]
	s_setprio 0
	s_barrier
	s_mov_b32 m0, s27
	v_lshl_add_u64 v[196:197], s[18:19], 0, v[2:3]
	s_add_u32 s14, s18, 0x160000
	ds_read_b128 v[164:167], v250 offset:16384
	ds_read_b128 v[168:171], v250 offset:17408
	ds_read_b128 v[172:175], v250 offset:18432
	ds_read_b128 v[176:179], v250 offset:19456
	ds_read_b128 v[180:183], v250 offset:20480
	ds_read_b128 v[184:187], v250 offset:21504
	ds_read_b128 v[188:191], v250 offset:22528
	ds_read_b128 v[192:195], v250 offset:23552
	global_load_lds_dwordx4 v[196:197], off
	v_lshl_add_u64 v[198:199], s[18:19], 0, v[216:217]
	s_mov_b32 m0, s37
	s_addc_u32 s15, s19, 0
	global_load_lds_dwordx4 v[198:199], off
	v_lshl_add_u64 v[200:201], s[14:15], 0, v[2:3]
	s_mov_b32 m0, s39
	v_lshl_add_u64 v[202:203], s[34:35], 0, v[218:219]
	global_load_lds_dwordx4 v[200:201], off
	v_lshl_add_u64 v[200:201], s[14:15], 0, v[216:217]
	s_mov_b32 m0, s40
	s_nop 0
	global_load_lds_dwordx4 v[200:201], off
	v_lshl_add_u64 v[200:201], s[34:35], 0, v[220:221]
	s_mov_b32 m0, s41
	s_nop 0
	global_load_lds_dwordx4 v[200:201], off
	s_mov_b32 m0, s42
	s_nop 0
	global_load_lds_dwordx4 v[202:203], off
	s_waitcnt vmcnt(8)
	s_waitcnt lgkmcnt(0)
	s_setprio 1
	s_barrier
	v_mfma_f32_16x16x32_bf16 v[64:67], v[132:135], v[164:167], v[64:67]
	v_mfma_f32_16x16x32_bf16 v[64:67], v[136:139], v[168:171], v[64:67]
	v_mfma_f32_16x16x32_bf16 v[48:51], v[132:135], v[172:175], v[48:51]
	v_mfma_f32_16x16x32_bf16 v[48:51], v[136:139], v[176:179], v[48:51]
	v_mfma_f32_16x16x32_bf16 v[32:35], v[132:135], v[180:183], v[32:35]
	v_mfma_f32_16x16x32_bf16 v[32:35], v[136:139], v[184:187], v[32:35]
	v_mfma_f32_16x16x32_bf16 v[16:19], v[132:135], v[188:191], v[16:19]
	v_mfma_f32_16x16x32_bf16 v[16:19], v[136:139], v[192:195], v[16:19]
	v_mfma_f32_16x16x32_bf16 v[12:15], v[140:143], v[188:191], v[12:15]
	v_mfma_f32_16x16x32_bf16 v[12:15], v[144:147], v[192:195], v[12:15]
	v_mfma_f32_16x16x32_bf16 v[28:31], v[140:143], v[180:183], v[28:31]
	v_mfma_f32_16x16x32_bf16 v[28:31], v[144:147], v[184:187], v[28:31]
	v_mfma_f32_16x16x32_bf16 v[44:47], v[140:143], v[172:175], v[44:47]
	v_mfma_f32_16x16x32_bf16 v[44:47], v[144:147], v[176:179], v[44:47]
	v_mfma_f32_16x16x32_bf16 v[60:63], v[140:143], v[164:167], v[60:63]
	v_mfma_f32_16x16x32_bf16 v[60:63], v[144:147], v[168:171], v[60:63]
	s_setprio 0
	s_setprio 1
	v_mfma_f32_16x16x32_bf16 v[56:59], v[148:151], v[164:167], v[56:59]
	v_mfma_f32_16x16x32_bf16 v[56:59], v[152:155], v[168:171], v[56:59]
	v_mfma_f32_16x16x32_bf16 v[40:43], v[148:151], v[172:175], v[40:43]
	v_mfma_f32_16x16x32_bf16 v[40:43], v[152:155], v[176:179], v[40:43]
	v_mfma_f32_16x16x32_bf16 v[24:27], v[148:151], v[180:183], v[24:27]
	v_mfma_f32_16x16x32_bf16 v[24:27], v[152:155], v[184:187], v[24:27]
	v_mfma_f32_16x16x32_bf16 v[8:11], v[148:151], v[188:191], v[8:11]
	v_mfma_f32_16x16x32_bf16 v[8:11], v[152:155], v[192:195], v[8:11]
	v_mfma_f32_16x16x32_bf16 v[4:7], v[156:159], v[188:191], v[4:7]
	v_mfma_f32_16x16x32_bf16 v[4:7], v[160:163], v[192:195], v[4:7]
	v_mfma_f32_16x16x32_bf16 v[20:23], v[156:159], v[180:183], v[20:23]
	v_mfma_f32_16x16x32_bf16 v[20:23], v[160:163], v[184:187], v[20:23]
	v_mfma_f32_16x16x32_bf16 v[36:39], v[156:159], v[172:175], v[36:39]
	v_mfma_f32_16x16x32_bf16 v[36:39], v[160:163], v[176:179], v[36:39]
	v_mfma_f32_16x16x32_bf16 v[52:55], v[156:159], v[164:167], v[52:55]
	v_mfma_f32_16x16x32_bf16 v[52:55], v[160:163], v[168:171], v[52:55]
	s_setprio 0
	s_barrier
	v_add_u32_e32 v144, s49, v249
	v_add_u32_e32 v160, s56, v249
	ds_read_b128 v[132:135], v144
	ds_read_b128 v[136:139], v144 offset:1024
	ds_read_b128 v[140:143], v144 offset:2048
	ds_read_b128 v[144:147], v144 offset:3072
	ds_read_b128 v[148:151], v160
	ds_read_b128 v[152:155], v160 offset:1024
	ds_read_b128 v[156:159], v160 offset:2048
	ds_read_b128 v[160:163], v160 offset:3072
	s_add_u32 s14, s34, 0x160000
	s_addc_u32 s15, s35, 0
	s_mov_b32 m0, s43
	v_lshl_add_u64 v[204:205], s[14:15], 0, v[220:221]
	ds_read_b128 v[164:167], v250 offset:32768
	ds_read_b128 v[168:171], v250 offset:33792
	ds_read_b128 v[172:175], v250 offset:34816
	ds_read_b128 v[176:179], v250 offset:35840
	ds_read_b128 v[180:183], v250 offset:36864
	ds_read_b128 v[184:187], v250 offset:37888
	ds_read_b128 v[188:191], v250 offset:38912
	ds_read_b128 v[192:195], v250 offset:39936
	global_load_lds_dwordx4 v[204:205], off
	v_lshl_add_u64 v[204:205], s[14:15], 0, v[218:219]
	s_mov_b32 m0, s44
	s_nop 0
	global_load_lds_dwordx4 v[204:205], off
	s_waitcnt vmcnt(8)
	s_waitcnt lgkmcnt(0)
	s_setprio 1
	s_barrier
	v_mfma_f32_16x16x32_bf16 v[128:131], v[132:135], v[164:167], v[128:131]
	v_mfma_f32_16x16x32_bf16 v[128:131], v[136:139], v[168:171], v[128:131]
	v_mfma_f32_16x16x32_bf16 v[112:115], v[132:135], v[172:175], v[112:115]
	v_mfma_f32_16x16x32_bf16 v[112:115], v[136:139], v[176:179], v[112:115]
	v_mfma_f32_16x16x32_bf16 v[96:99], v[132:135], v[180:183], v[96:99]
	v_mfma_f32_16x16x32_bf16 v[96:99], v[136:139], v[184:187], v[96:99]
	v_mfma_f32_16x16x32_bf16 v[80:83], v[132:135], v[188:191], v[80:83]
	v_mfma_f32_16x16x32_bf16 v[80:83], v[136:139], v[192:195], v[80:83]
	v_mfma_f32_16x16x32_bf16 v[76:79], v[140:143], v[188:191], v[76:79]
	v_mfma_f32_16x16x32_bf16 v[76:79], v[144:147], v[192:195], v[76:79]
	v_mfma_f32_16x16x32_bf16 v[92:95], v[140:143], v[180:183], v[92:95]
	v_mfma_f32_16x16x32_bf16 v[92:95], v[144:147], v[184:187], v[92:95]
	v_mfma_f32_16x16x32_bf16 v[108:111], v[140:143], v[172:175], v[108:111]
	v_mfma_f32_16x16x32_bf16 v[108:111], v[144:147], v[176:179], v[108:111]
	v_mfma_f32_16x16x32_bf16 v[124:127], v[140:143], v[164:167], v[124:127]
	v_mfma_f32_16x16x32_bf16 v[124:127], v[144:147], v[168:171], v[124:127]
	s_setprio 0
	s_setprio 1
	v_mfma_f32_16x16x32_bf16 v[120:123], v[148:151], v[164:167], v[120:123]
	v_mfma_f32_16x16x32_bf16 v[120:123], v[152:155], v[168:171], v[120:123]
	v_mfma_f32_16x16x32_bf16 v[104:107], v[148:151], v[172:175], v[104:107]
	v_mfma_f32_16x16x32_bf16 v[104:107], v[152:155], v[176:179], v[104:107]
	v_mfma_f32_16x16x32_bf16 v[88:91], v[148:151], v[180:183], v[88:91]
	v_mfma_f32_16x16x32_bf16 v[88:91], v[152:155], v[184:187], v[88:91]
	v_mfma_f32_16x16x32_bf16 v[72:75], v[148:151], v[188:191], v[72:75]
	v_mfma_f32_16x16x32_bf16 v[72:75], v[152:155], v[192:195], v[72:75]
	v_mfma_f32_16x16x32_bf16 v[68:71], v[156:159], v[188:191], v[68:71]
	v_mfma_f32_16x16x32_bf16 v[68:71], v[160:163], v[192:195], v[68:71]
	v_mfma_f32_16x16x32_bf16 v[84:87], v[156:159], v[180:183], v[84:87]
	v_mfma_f32_16x16x32_bf16 v[84:87], v[160:163], v[184:187], v[84:87]
	v_mfma_f32_16x16x32_bf16 v[100:103], v[156:159], v[172:175], v[100:103]
	v_mfma_f32_16x16x32_bf16 v[100:103], v[160:163], v[176:179], v[100:103]
	v_mfma_f32_16x16x32_bf16 v[116:119], v[156:159], v[164:167], v[116:119]
	v_mfma_f32_16x16x32_bf16 v[116:119], v[160:163], v[168:171], v[116:119]
	s_setprio 0
	s_barrier
	s_mov_b32 m0, s50
	v_lshl_add_u64 v[196:197], v[196:197], 0, s[64:65]
	s_add_u32 s14, s18, 0x160080
	ds_read_b128 v[164:167], v250 offset:49152
	ds_read_b128 v[168:171], v250 offset:50176
	ds_read_b128 v[172:175], v250 offset:51200
	ds_read_b128 v[176:179], v250 offset:52224
	ds_read_b128 v[180:183], v250 offset:53248
	ds_read_b128 v[184:187], v250 offset:54272
	ds_read_b128 v[188:191], v250 offset:55296
	ds_read_b128 v[192:195], v250 offset:56320
	global_load_lds_dwordx4 v[196:197], off
	v_lshl_add_u64 v[196:197], v[198:199], 0, s[64:65]
	s_mov_b32 m0, s51
	s_addc_u32 s15, s19, 0
	global_load_lds_dwordx4 v[196:197], off
	v_lshl_add_u64 v[196:197], s[14:15], 0, v[2:3]
	s_mov_b32 m0, s57
	s_nop 0
	global_load_lds_dwordx4 v[196:197], off
	v_lshl_add_u64 v[196:197], s[14:15], 0, v[216:217]
	s_mov_b32 m0, s58
	s_nop 0
	global_load_lds_dwordx4 v[196:197], off
	v_lshl_add_u64 v[196:197], v[200:201], 0, s[64:65]
	s_mov_b32 m0, s52
	s_nop 0
	global_load_lds_dwordx4 v[196:197], off
	v_lshl_add_u64 v[196:197], v[202:203], 0, s[64:65]
	s_mov_b32 m0, s53
	s_nop 0
	global_load_lds_dwordx4 v[196:197], off
	s_waitcnt vmcnt(8)
	s_waitcnt lgkmcnt(0)
	s_setprio 1
	s_barrier
	v_mfma_f32_16x16x32_bf16 v[64:67], v[132:135], v[164:167], v[64:67]
	v_mfma_f32_16x16x32_bf16 v[64:67], v[136:139], v[168:171], v[64:67]
	v_mfma_f32_16x16x32_bf16 v[48:51], v[132:135], v[172:175], v[48:51]
	v_mfma_f32_16x16x32_bf16 v[48:51], v[136:139], v[176:179], v[48:51]
	v_mfma_f32_16x16x32_bf16 v[32:35], v[132:135], v[180:183], v[32:35]
	v_mfma_f32_16x16x32_bf16 v[32:35], v[136:139], v[184:187], v[32:35]
	v_mfma_f32_16x16x32_bf16 v[16:19], v[132:135], v[188:191], v[16:19]
	v_mfma_f32_16x16x32_bf16 v[16:19], v[136:139], v[192:195], v[16:19]
	v_mfma_f32_16x16x32_bf16 v[12:15], v[140:143], v[188:191], v[12:15]
	v_mfma_f32_16x16x32_bf16 v[12:15], v[144:147], v[192:195], v[12:15]
	v_mfma_f32_16x16x32_bf16 v[28:31], v[140:143], v[180:183], v[28:31]
	v_mfma_f32_16x16x32_bf16 v[28:31], v[144:147], v[184:187], v[28:31]
	v_mfma_f32_16x16x32_bf16 v[44:47], v[140:143], v[172:175], v[44:47]
	v_mfma_f32_16x16x32_bf16 v[44:47], v[144:147], v[176:179], v[44:47]
	v_mfma_f32_16x16x32_bf16 v[60:63], v[140:143], v[164:167], v[60:63]
	v_mfma_f32_16x16x32_bf16 v[60:63], v[144:147], v[168:171], v[60:63]
	s_setprio 0
	s_setprio 1
	v_mfma_f32_16x16x32_bf16 v[56:59], v[148:151], v[164:167], v[56:59]
	v_mfma_f32_16x16x32_bf16 v[56:59], v[152:155], v[168:171], v[56:59]
	v_mfma_f32_16x16x32_bf16 v[40:43], v[148:151], v[172:175], v[40:43]
	v_mfma_f32_16x16x32_bf16 v[40:43], v[152:155], v[176:179], v[40:43]
	v_mfma_f32_16x16x32_bf16 v[24:27], v[148:151], v[180:183], v[24:27]
	v_mfma_f32_16x16x32_bf16 v[24:27], v[152:155], v[184:187], v[24:27]
	v_mfma_f32_16x16x32_bf16 v[8:11], v[148:151], v[188:191], v[8:11]
	v_mfma_f32_16x16x32_bf16 v[8:11], v[152:155], v[192:195], v[8:11]
	s_add_i32 s74, s74, 2
	v_mfma_f32_16x16x32_bf16 v[4:7], v[156:159], v[188:191], v[4:7]
	v_mfma_f32_16x16x32_bf16 v[4:7], v[160:163], v[192:195], v[4:7]
	s_add_u32 s71, s71, 0x100
	s_addc_u32 s73, s73, 0
	v_mfma_f32_16x16x32_bf16 v[20:23], v[156:159], v[180:183], v[20:23]
	v_mfma_f32_16x16x32_bf16 v[20:23], v[160:163], v[184:187], v[20:23]
	s_cmpk_gt_u32 s74, 0x55
	v_mfma_f32_16x16x32_bf16 v[36:39], v[156:159], v[172:175], v[36:39]
	v_mfma_f32_16x16x32_bf16 v[36:39], v[160:163], v[176:179], v[36:39]
	v_mfma_f32_16x16x32_bf16 v[52:55], v[156:159], v[164:167], v[52:55]
	v_mfma_f32_16x16x32_bf16 v[52:55], v[160:163], v[168:171], v[52:55]
	s_setprio 0
	s_barrier
	s_mov_b64 s[14:15], s[24:25]
	s_cbranch_scc0 .LBB0_3195
	s_and_b64 vcc, exec, s[10:11]
	s_cbranch_vccz .LBB0_3198
	s_barrier
